# v22 + first K-loop trip of every GEMM unit peeled with C = 0 on each accumulator's first MFMA; the 128 zeroing moves per unit removed
# speedup vs baseline: 1.0111x; 1.0111x over previous
; #define PG8_BAR __builtin_amdgcn_s_barrier()
; template <class Epi, class Sched, bool ALIGN_EPI = false, bool SP2 = false>
; __device__ __forceinline__ void gemm_phase(PG8_LAS unsigned char* lds, const Gemm g, const Sched& S, const Epi& E, int tid_in) {
;     ...
;         const bool has_next = S.next(ui + 1, nxt);
;         const char* nA = has_next ? (const char*)g.A + (size_t)nxt.pm * tstep : cA; const char* nB = has_next ? (const char*)g.Bt + (size_t)nxt.pn * tstep : cB;
;         for (int t = 0; t < nt; t += 2) {
;             if constexpr (Epi::MIDK) { if (t == Epi::MIDK_T) { if (wr == 0) PG8_BAR; E.mid(acc, cur, wr, wc, fr, fq); if (wr == 1) PG8_BAR; } }
;             const bool last = (t == nt - 2);
;             const char* a1 = cA + (size_t)(t + 1) * kstep;
;             const char* a2 = last ? nA : cA + (size_t)(t + 2) * kstep; const char* b2 = last ? nB : cB + (size_t)(t + 2) * kstep;
;             const char* a3 = a2 + kstep; const char* b3 = b2 + kstep;
;             if (last && has_next) S.a_ready(nxt);
;             if constexpr (SP2) {
;             PG8_LDB(B0, 0, 0); PG8_LDB(B1, 0, 1); PG8_SCHED; PG8_LDA(At, 0, 0); PG8_STAGE(PG8_SA(1, 1), a1 + hstep, voffA);
;             PG8_WAIT_V(8); PG8_WAIT_L(0); PG8_BAR; PG8_MMA(0, 0, At, B0); PG8_MMA(0, 1, At, B1); PG8_BAR; PG8_SCHED;
;             PG8_LDA(At, 0, 1); PG8_STAGE(PG8_SB(0, 0), b2, voffB); PG8_STAGE(PG8_SB(0, 1), b2 + hstep, voffB); PG8_STAGE(PG8_SA(0, 0), a2, voffA);
;             PG8_WAIT_V(8); PG8_WAIT_L(0); PG8_BAR; PG8_MMA(1, 0, At, B0); PG8_MMA(1, 1, At, B1); PG8_BAR; PG8_SCHED;
;             PG8_LDB(B0, 1, 0); PG8_LDB(B1, 1, 1); PG8_SCHED; PG8_LDA(At, 1, 0); PG8_STAGE(PG8_SA(0, 1), a2 + hstep, voffA);
;             PG8_WAIT_V(8); PG8_WAIT_L(0); PG8_BAR; PG8_MMA(0, 0, At, B0); PG8_MMA(0, 1, At, B1); PG8_BAR; PG8_SCHED;
;             PG8_LDA(At, 1, 1); PG8_STAGE(PG8_SB(1, 0), b3, voffB); PG8_STAGE(PG8_SB(1, 1), b3 + hstep, voffB); PG8_STAGE(PG8_SA(1, 0), a3, voffA);
;             PG8_WAIT_V(8); PG8_WAIT_L(0); PG8_BAR; PG8_MMA(1, 0, At, B0); PG8_MMA(1, 1, At, B1); PG8_BAR; PG8_SCHED;
;     ...
; #pragma unroll
;         for (int a = 0; a < 2; ++a)
; #pragma unroll
;             for (int b = 0; b < 2; ++b)
; #pragma unroll
;                 for (int m = 0; m < 4; ++m)
; #pragma unroll
;                     for (int n = 0; n < 2; ++n) acc[a][b][m][n] = (f32x4){0.f, 0.f, 0.f, 0.f};
.LBB0_375:
	s_ashr_i32 s17, s16, 31
	s_lshl_b64 s[18:19], s[16:17], 19
	s_add_u32 s18, s0, s18
	s_addc_u32 s19, s1, s19
	s_and_b64 s[20:21], s[2:3], exec
	s_cselect_b32 s17, s19, s25
	s_cselect_b32 s52, s18, s24
	s_ashr_i32 s15, s14, 31
	s_lshl_b64 s[20:21], s[14:15], 19
	s_add_u32 s20, s30, s20
	s_addc_u32 s21, s31, s21
	s_and_b64 s[28:29], s[2:3], exec
	s_cselect_b32 s15, s21, s27
	s_cselect_b32 s53, s20, s26
	s_add_u32 s24, s24, 0x40080
	s_addc_u32 s25, s25, 0
	s_add_u32 s54, s26, 0x100
	s_addc_u32 s55, s27, 0
	s_mov_b32 s56, -2
	s_add_u32 s26, s24, 0xfffc0080
	s_addc_u32 s27, s25, -1
	s_cmp_eq_u32 s56, 12
	s_cselect_b32 s29, s17, s27
	s_cselect_b32 s28, s52, s26
	s_cselect_b32 s27, s15, s55
	s_cselect_b32 s26, s53, s54
	s_add_i32 m0, s23, 0xc000
	ds_read_b128 v[150:153], v147
	global_load_lds_dwordx4 v136, s[24:25]
	s_add_i32 m0, s23, 0xe000
	ds_read_b128 v[154:157], v147 offset:1024
	global_load_lds_dwordx4 v138, s[24:25]
	ds_read_b128 v[158:161], v147 offset:2048
	ds_read_b128 v[162:165], v147 offset:3072
	ds_read_b128 v[166:169], v148
	ds_read_b128 v[170:173], v148 offset:1024
	ds_read_b128 v[174:177], v148 offset:2048
	ds_read_b128 v[178:181], v148 offset:3072
	ds_read_b128 v[182:185], v149
	ds_read_b128 v[186:189], v149 offset:1024
	ds_read_b128 v[190:193], v149 offset:2048
	ds_read_b128 v[194:197], v149 offset:3072
	ds_read_b128 v[198:201], v149 offset:4096
	ds_read_b128 v[202:205], v149 offset:5120
	ds_read_b128 v[206:209], v149 offset:6144
	ds_read_b128 v[210:213], v149 offset:7168
	s_waitcnt vmcnt(8)
	s_waitcnt lgkmcnt(0)
	s_barrier
	v_mfma_f32_16x16x32_bf16 v[124:127], v[150:153], v[182:185], 0
	v_mfma_f32_16x16x32_bf16 v[120:123], v[158:161], v[182:185], 0
	v_mfma_f32_16x16x32_bf16 v[108:111], v[150:153], v[190:193], 0
	v_mfma_f32_16x16x32_bf16 v[104:107], v[158:161], v[190:193], 0
	v_mfma_f32_16x16x32_bf16 v[92:95], v[150:153], v[198:201], 0
	v_mfma_f32_16x16x32_bf16 v[88:91], v[158:161], v[198:201], 0
	v_mfma_f32_16x16x32_bf16 v[76:79], v[150:153], v[206:209], 0
	v_mfma_f32_16x16x32_bf16 v[72:75], v[158:161], v[206:209], 0
	v_mfma_f32_16x16x32_bf16 v[124:127], v[154:157], v[186:189], v[124:127]
	v_mfma_f32_16x16x32_bf16 v[120:123], v[162:165], v[186:189], v[120:123]
	v_mfma_f32_16x16x32_bf16 v[108:111], v[154:157], v[194:197], v[108:111]
	v_mfma_f32_16x16x32_bf16 v[104:107], v[162:165], v[194:197], v[104:107]
	v_mfma_f32_16x16x32_bf16 v[92:95], v[154:157], v[202:205], v[92:95]
	v_mfma_f32_16x16x32_bf16 v[88:91], v[162:165], v[202:205], v[88:91]
	v_mfma_f32_16x16x32_bf16 v[76:79], v[154:157], v[210:213], v[76:79]
	v_mfma_f32_16x16x32_bf16 v[72:75], v[162:165], v[210:213], v[72:75]
	v_mfma_f32_16x16x32_bf16 v[116:119], v[166:169], v[182:185], 0
	v_mfma_f32_16x16x32_bf16 v[112:115], v[174:177], v[182:185], 0
	v_mfma_f32_16x16x32_bf16 v[100:103], v[166:169], v[190:193], 0
	v_mfma_f32_16x16x32_bf16 v[96:99], v[174:177], v[190:193], 0
	v_mfma_f32_16x16x32_bf16 v[84:87], v[166:169], v[198:201], 0
	v_mfma_f32_16x16x32_bf16 v[80:83], v[174:177], v[198:201], 0
	v_mfma_f32_16x16x32_bf16 v[68:71], v[166:169], v[206:209], 0
	v_mfma_f32_16x16x32_bf16 v[64:67], v[174:177], v[206:209], 0
	v_mfma_f32_16x16x32_bf16 v[116:119], v[170:173], v[186:189], v[116:119]
	v_mfma_f32_16x16x32_bf16 v[112:115], v[178:181], v[186:189], v[112:115]
	v_mfma_f32_16x16x32_bf16 v[100:103], v[170:173], v[194:197], v[100:103]
	v_mfma_f32_16x16x32_bf16 v[96:99], v[178:181], v[194:197], v[96:99]
	v_mfma_f32_16x16x32_bf16 v[84:87], v[170:173], v[202:205], v[84:87]
	v_mfma_f32_16x16x32_bf16 v[80:83], v[178:181], v[202:205], v[80:83]
	v_mfma_f32_16x16x32_bf16 v[68:71], v[170:173], v[210:213], v[68:71]
	v_mfma_f32_16x16x32_bf16 v[64:67], v[178:181], v[210:213], v[64:67]
	s_barrier
	s_add_u32 s98, s26, s10
	s_addc_u32 s99, s27, s11
	s_add_u32 s100, s28, s10
	s_addc_u32 s101, s29, s11
	s_add_i32 s57, s48, s34
	s_mov_b32 m0, s57
	ds_read_b128 v[182:185], v149 offset:16384
	global_load_lds_dwordx4 v132, s[26:27]
	s_add_i32 m0, s57, 0x2000
	s_add_u32 s60, s26, 0x40000
	s_addc_u32 s61, s27, 0
	s_add_i32 s57, s49, s34
	global_load_lds_dwordx4 v128, s[26:27]
	s_mov_b32 m0, s57
	ds_read_b128 v[186:189], v149 offset:17408
	global_load_lds_dwordx4 v132, s[60:61]
	s_add_i32 m0, s57, 0x2000
	ds_read_b128 v[190:193], v149 offset:18432
	global_load_lds_dwordx4 v128, s[60:61]
	s_mov_b32 m0, s23
	ds_read_b128 v[194:197], v149 offset:19456
	global_load_lds_dwordx4 v134, s[28:29]
	s_mov_b32 m0, s37
	ds_read_b128 v[198:201], v149 offset:20480
	global_load_lds_dwordx4 v130, s[28:29]
	ds_read_b128 v[202:205], v149 offset:21504
	ds_read_b128 v[206:209], v149 offset:22528
	ds_read_b128 v[210:213], v149 offset:23552
	s_waitcnt vmcnt(8)
	s_waitcnt lgkmcnt(0)
	s_barrier
; #define PG8_STAGE(bufoff, gbase, voff) do { _Pragma("unroll") for (int _i = 0; _i < 2; ++_i) \
;         __builtin_amdgcn_global_load_lds((const unsigned*)((const char*)(gbase) + (voff)[_i]), (PG8_LAS unsigned*)(lds + (bufoff) + ldsw + _i * 8192), 16, 0, 0); } while (0)
; #define PG8_LDA(dst, b, h) do { _Pragma("unroll") for (int m = 0; m < 4; ++m) _Pragma("unroll") for (int k = 0; k < 2; ++k) dst[m][k] = *(const PG8_LAS bf16x8*)(lds + PG8_SA(b, h) + aoff + m * 2048 + k * 1024); } while (0)
; #define PG8_LDB(dst, b, h) do { _Pragma("unroll") for (int n = 0; n < 2; ++n) _Pragma("unroll") for (int k = 0; k < 2; ++k) dst[n][k] = *(const PG8_LAS bf16x8*)(lds + PG8_SB(b, h) + boff + n * 2048 + k * 1024); } while (0)
; #define PG8_MMA(ai, bj, At, Bt) do { __builtin_amdgcn_s_setprio(1); _Pragma("unroll") for (int m = 0; m < 4; ++m) _Pragma("unroll") for (int n = 0; n < 2; ++n) _Pragma("unroll") for (int k = 0; k < 2; ++k) \
;         acc[ai][bj][m][n] = __builtin_amdgcn_mfma_f32_16x16x32_bf16(Bt[n][k], At[m][k], acc[ai][bj][m][n], 0, 0, 0); __builtin_amdgcn_s_setprio(0); } while (0)
; #define PG8_BAR __builtin_amdgcn_s_barrier()
; template <class Epi, class Sched, bool ALIGN_EPI = false, bool SP2 = false>
; __device__ __forceinline__ void gemm_phase(PG8_LAS unsigned char* lds, const Gemm g, const Sched& S, const Epi& E, int tid_in) {
;     ...
;             PG8_LDB(B0, 0, 0); PG8_LDB(B1, 0, 1); PG8_SCHED; PG8_LDA(At, 0, 0); PG8_STAGE(PG8_SA(1, 1), a1 + hstep, voffA);
;             PG8_WAIT_V(8); PG8_WAIT_L(0); PG8_BAR; PG8_MMA(0, 0, At, B0); PG8_MMA(0, 1, At, B1); PG8_BAR; PG8_SCHED;
;             PG8_LDA(At, 0, 1); PG8_STAGE(PG8_SB(0, 0), b2, voffB); PG8_STAGE(PG8_SB(0, 1), b2 + hstep, voffB); PG8_STAGE(PG8_SA(0, 0), a2, voffA);
;             PG8_WAIT_V(8); PG8_WAIT_L(0); PG8_BAR; PG8_MMA(1, 0, At, B0); PG8_MMA(1, 1, At, B1); PG8_BAR; PG8_SCHED;
;             PG8_LDB(B0, 1, 0); PG8_LDB(B1, 1, 1); PG8_SCHED; PG8_LDA(At, 1, 0); PG8_STAGE(PG8_SA(0, 1), a2 + hstep, voffA);
;             PG8_WAIT_V(8); PG8_WAIT_L(0); PG8_BAR; PG8_MMA(0, 0, At, B0); PG8_MMA(0, 1, At, B1); PG8_BAR; PG8_SCHED;
;             PG8_LDA(At, 1, 1); PG8_STAGE(PG8_SB(1, 0), b3, voffB); PG8_STAGE(PG8_SB(1, 1), b3 + hstep, voffB); PG8_STAGE(PG8_SA(1, 0), a3, voffA);
;             PG8_WAIT_V(8); PG8_WAIT_L(0); PG8_BAR; PG8_MMA(1, 0, At, B0); PG8_MMA(1, 1, At, B1); PG8_BAR; PG8_SCHED;
	v_mfma_f32_16x16x32_bf16 v[60:63], v[150:153], v[182:185], 0
	v_mfma_f32_16x16x32_bf16 v[56:59], v[158:161], v[182:185], 0
	v_mfma_f32_16x16x32_bf16 v[44:47], v[150:153], v[190:193], 0
	v_mfma_f32_16x16x32_bf16 v[40:43], v[158:161], v[190:193], 0
	v_mfma_f32_16x16x32_bf16 v[28:31], v[150:153], v[198:201], 0
	v_mfma_f32_16x16x32_bf16 v[24:27], v[158:161], v[198:201], 0
	v_mfma_f32_16x16x32_bf16 v[12:15], v[150:153], v[206:209], 0
	v_mfma_f32_16x16x32_bf16 v[8:11], v[158:161], v[206:209], 0
	v_mfma_f32_16x16x32_bf16 v[60:63], v[154:157], v[186:189], v[60:63]
	v_mfma_f32_16x16x32_bf16 v[56:59], v[162:165], v[186:189], v[56:59]
	v_mfma_f32_16x16x32_bf16 v[44:47], v[154:157], v[194:197], v[44:47]
	v_mfma_f32_16x16x32_bf16 v[40:43], v[162:165], v[194:197], v[40:43]
	v_mfma_f32_16x16x32_bf16 v[28:31], v[154:157], v[202:205], v[28:31]
	v_mfma_f32_16x16x32_bf16 v[24:27], v[162:165], v[202:205], v[24:27]
	v_mfma_f32_16x16x32_bf16 v[12:15], v[154:157], v[210:213], v[12:15]
	v_mfma_f32_16x16x32_bf16 v[8:11], v[162:165], v[210:213], v[8:11]
	v_mfma_f32_16x16x32_bf16 v[52:55], v[166:169], v[182:185], 0
	v_mfma_f32_16x16x32_bf16 v[48:51], v[174:177], v[182:185], 0
	v_mfma_f32_16x16x32_bf16 v[36:39], v[166:169], v[190:193], 0
	v_mfma_f32_16x16x32_bf16 v[32:35], v[174:177], v[190:193], 0
	v_mfma_f32_16x16x32_bf16 v[20:23], v[166:169], v[198:201], 0
	v_mfma_f32_16x16x32_bf16 v[16:19], v[174:177], v[198:201], 0
	v_mfma_f32_16x16x32_bf16 v[4:7], v[166:169], v[206:209], 0
	v_mfma_f32_16x16x32_bf16 v[0:3], v[174:177], v[206:209], 0
	v_mfma_f32_16x16x32_bf16 v[52:55], v[170:173], v[186:189], v[52:55]
	v_mfma_f32_16x16x32_bf16 v[48:51], v[178:181], v[186:189], v[48:51]
	v_mfma_f32_16x16x32_bf16 v[36:39], v[170:173], v[194:197], v[36:39]
	v_mfma_f32_16x16x32_bf16 v[32:35], v[178:181], v[194:197], v[32:35]
	v_mfma_f32_16x16x32_bf16 v[20:23], v[170:173], v[202:205], v[20:23]
	v_mfma_f32_16x16x32_bf16 v[16:19], v[178:181], v[202:205], v[16:19]
	v_mfma_f32_16x16x32_bf16 v[4:7], v[170:173], v[210:213], v[4:7]
	v_mfma_f32_16x16x32_bf16 v[0:3], v[178:181], v[210:213], v[0:3]
	s_barrier
	s_add_i32 s57, 0, 0x18000
	s_add_i32 s59, 0, 0x1c000
	s_add_u32 s28, s28, 0x40000
	s_addc_u32 s29, s29, 0
	s_mov_b32 m0, s38
	s_nop 0
	global_load_lds_dwordx4 v134, s[28:29]
	s_mov_b32 m0, s39
	s_nop 0
	global_load_lds_dwordx4 v130, s[28:29]
	v_add_u32_e32 v162, s57, v145
	v_add_u32_e32 v178, s59, v145
	ds_read_b128 v[150:153], v162
	ds_read_b128 v[154:157], v162 offset:1024
	ds_read_b128 v[158:161], v162 offset:2048
	ds_read_b128 v[162:165], v162 offset:3072
	ds_read_b128 v[166:169], v178
	ds_read_b128 v[170:173], v178 offset:1024
	ds_read_b128 v[174:177], v178 offset:2048
	ds_read_b128 v[178:181], v178 offset:3072
	ds_read_b128 v[182:185], v149 offset:32768
	ds_read_b128 v[186:189], v149 offset:33792
	ds_read_b128 v[190:193], v149 offset:34816
	ds_read_b128 v[194:197], v149 offset:35840
	ds_read_b128 v[198:201], v149 offset:36864
	ds_read_b128 v[202:205], v149 offset:37888
	ds_read_b128 v[206:209], v149 offset:38912
	ds_read_b128 v[210:213], v149 offset:39936
	s_waitcnt vmcnt(8)
	s_waitcnt lgkmcnt(0)
	s_barrier
	v_mfma_f32_16x16x32_bf16 v[124:127], v[150:153], v[182:185], v[124:127]
	v_mfma_f32_16x16x32_bf16 v[120:123], v[158:161], v[182:185], v[120:123]
	v_mfma_f32_16x16x32_bf16 v[108:111], v[150:153], v[190:193], v[108:111]
	v_mfma_f32_16x16x32_bf16 v[104:107], v[158:161], v[190:193], v[104:107]
	v_mfma_f32_16x16x32_bf16 v[92:95], v[150:153], v[198:201], v[92:95]
	v_mfma_f32_16x16x32_bf16 v[88:91], v[158:161], v[198:201], v[88:91]
	v_mfma_f32_16x16x32_bf16 v[76:79], v[150:153], v[206:209], v[76:79]
	v_mfma_f32_16x16x32_bf16 v[72:75], v[158:161], v[206:209], v[72:75]
	v_mfma_f32_16x16x32_bf16 v[124:127], v[154:157], v[186:189], v[124:127]
	v_mfma_f32_16x16x32_bf16 v[120:123], v[162:165], v[186:189], v[120:123]
	v_mfma_f32_16x16x32_bf16 v[108:111], v[154:157], v[194:197], v[108:111]
	v_mfma_f32_16x16x32_bf16 v[104:107], v[162:165], v[194:197], v[104:107]
	v_mfma_f32_16x16x32_bf16 v[92:95], v[154:157], v[202:205], v[92:95]
	v_mfma_f32_16x16x32_bf16 v[88:91], v[162:165], v[202:205], v[88:91]
	v_mfma_f32_16x16x32_bf16 v[76:79], v[154:157], v[210:213], v[76:79]
	v_mfma_f32_16x16x32_bf16 v[72:75], v[162:165], v[210:213], v[72:75]
	v_mfma_f32_16x16x32_bf16 v[116:119], v[166:169], v[182:185], v[116:119]
	v_mfma_f32_16x16x32_bf16 v[112:115], v[174:177], v[182:185], v[112:115]
	v_mfma_f32_16x16x32_bf16 v[100:103], v[166:169], v[190:193], v[100:103]
	v_mfma_f32_16x16x32_bf16 v[96:99], v[174:177], v[190:193], v[96:99]
	v_mfma_f32_16x16x32_bf16 v[84:87], v[166:169], v[198:201], v[84:87]
	v_mfma_f32_16x16x32_bf16 v[80:83], v[174:177], v[198:201], v[80:83]
	v_mfma_f32_16x16x32_bf16 v[68:71], v[166:169], v[206:209], v[68:71]
	v_mfma_f32_16x16x32_bf16 v[64:67], v[174:177], v[206:209], v[64:67]
	v_mfma_f32_16x16x32_bf16 v[116:119], v[170:173], v[186:189], v[116:119]
	v_mfma_f32_16x16x32_bf16 v[112:115], v[178:181], v[186:189], v[112:115]
	v_mfma_f32_16x16x32_bf16 v[100:103], v[170:173], v[194:197], v[100:103]
	v_mfma_f32_16x16x32_bf16 v[96:99], v[178:181], v[194:197], v[96:99]
	v_mfma_f32_16x16x32_bf16 v[84:87], v[170:173], v[202:205], v[84:87]
	v_mfma_f32_16x16x32_bf16 v[80:83], v[178:181], v[202:205], v[80:83]
	v_mfma_f32_16x16x32_bf16 v[68:71], v[170:173], v[210:213], v[68:71]
	v_mfma_f32_16x16x32_bf16 v[64:67], v[178:181], v[210:213], v[64:67]
	s_barrier
; #define PG8_STAGE(bufoff, gbase, voff) do { _Pragma("unroll") for (int _i = 0; _i < 2; ++_i) \
;         __builtin_amdgcn_global_load_lds((const unsigned*)((const char*)(gbase) + (voff)[_i]), (PG8_LAS unsigned*)(lds + (bufoff) + ldsw + _i * 8192), 16, 0, 0); } while (0)
; #define PG8_LDA(dst, b, h) do { _Pragma("unroll") for (int m = 0; m < 4; ++m) _Pragma("unroll") for (int k = 0; k < 2; ++k) dst[m][k] = *(const PG8_LAS bf16x8*)(lds + PG8_SA(b, h) + aoff + m * 2048 + k * 1024); } while (0)
; #define PG8_MMA(ai, bj, At, Bt) do { __builtin_amdgcn_s_setprio(1); _Pragma("unroll") for (int m = 0; m < 4; ++m) _Pragma("unroll") for (int n = 0; n < 2; ++n) _Pragma("unroll") for (int k = 0; k < 2; ++k) \
;         acc[ai][bj][m][n] = __builtin_amdgcn_mfma_f32_16x16x32_bf16(Bt[n][k], At[m][k], acc[ai][bj][m][n], 0, 0, 0); __builtin_amdgcn_s_setprio(0); } while (0)
; #define PG8_WAIT_V(n) asm volatile("s_waitcnt vmcnt(" #n ")" ::: "memory")
; #define PG8_WAIT_L(n) asm volatile("s_waitcnt lgkmcnt(" #n ")" ::: "memory")
; #define PG8_BAR __builtin_amdgcn_s_barrier()
; #define PG8_SCHED __builtin_amdgcn_sched_barrier(0)
; template <class Epi, class Sched, bool ALIGN_EPI = false, bool SP2 = false>
; __device__ __forceinline__ void gemm_phase(PG8_LAS unsigned char* lds, const Gemm g, const Sched& S, const Epi& E, int tid_in) {
;     ...
;             PG8_LDA(At, 1, 1); PG8_STAGE(PG8_SB(1, 0), b3, voffB); PG8_STAGE(PG8_SB(1, 1), b3 + hstep, voffB); PG8_STAGE(PG8_SA(1, 0), a3, voffA);
;             PG8_WAIT_V(8); PG8_WAIT_L(0); PG8_BAR; PG8_MMA(1, 0, At, B0); PG8_MMA(1, 1, At, B1); PG8_BAR; PG8_SCHED;
	s_add_i32 s28, s57, s34
	s_mov_b32 m0, s28
	ds_read_b128 v[182:185], v149 offset:49152
	global_load_lds_dwordx4 v132, s[98:99]
	s_add_i32 m0, s28, 0x2000
	s_add_u32 s26, s26, 0x40080
	s_addc_u32 s27, s27, 0
	s_add_i32 s28, s59, s34
	global_load_lds_dwordx4 v128, s[98:99]
	s_mov_b32 m0, s28
	ds_read_b128 v[186:189], v149 offset:50176
	global_load_lds_dwordx4 v132, s[26:27]
	s_add_i32 m0, s28, 0x2000
	ds_read_b128 v[190:193], v149 offset:51200
	global_load_lds_dwordx4 v128, s[26:27]
	s_mov_b32 m0, s44
	ds_read_b128 v[194:197], v149 offset:52224
	global_load_lds_dwordx4 v134, s[100:101]
	s_mov_b32 m0, s45
	ds_read_b128 v[198:201], v149 offset:53248
	global_load_lds_dwordx4 v130, s[100:101]
	ds_read_b128 v[202:205], v149 offset:54272
	ds_read_b128 v[206:209], v149 offset:55296
	ds_read_b128 v[210:213], v149 offset:56320
	s_waitcnt vmcnt(8)
	s_waitcnt lgkmcnt(0)
	s_barrier
	v_mfma_f32_16x16x32_bf16 v[60:63], v[150:153], v[182:185], v[60:63]
	v_mfma_f32_16x16x32_bf16 v[56:59], v[158:161], v[182:185], v[56:59]
	v_mfma_f32_16x16x32_bf16 v[44:47], v[150:153], v[190:193], v[44:47]
	v_mfma_f32_16x16x32_bf16 v[40:43], v[158:161], v[190:193], v[40:43]
	v_mfma_f32_16x16x32_bf16 v[28:31], v[150:153], v[198:201], v[28:31]
	v_mfma_f32_16x16x32_bf16 v[24:27], v[158:161], v[198:201], v[24:27]
	v_mfma_f32_16x16x32_bf16 v[12:15], v[150:153], v[206:209], v[12:15]
	v_mfma_f32_16x16x32_bf16 v[8:11], v[158:161], v[206:209], v[8:11]
	v_mfma_f32_16x16x32_bf16 v[60:63], v[154:157], v[186:189], v[60:63]
	v_mfma_f32_16x16x32_bf16 v[56:59], v[162:165], v[186:189], v[56:59]
	v_mfma_f32_16x16x32_bf16 v[44:47], v[154:157], v[194:197], v[44:47]
	v_mfma_f32_16x16x32_bf16 v[40:43], v[162:165], v[194:197], v[40:43]
	v_mfma_f32_16x16x32_bf16 v[28:31], v[154:157], v[202:205], v[28:31]
	v_mfma_f32_16x16x32_bf16 v[24:27], v[162:165], v[202:205], v[24:27]
	v_mfma_f32_16x16x32_bf16 v[12:15], v[154:157], v[210:213], v[12:15]
	v_mfma_f32_16x16x32_bf16 v[8:11], v[162:165], v[210:213], v[8:11]
	v_mfma_f32_16x16x32_bf16 v[52:55], v[166:169], v[182:185], v[52:55]
	v_mfma_f32_16x16x32_bf16 v[48:51], v[174:177], v[182:185], v[48:51]
	v_mfma_f32_16x16x32_bf16 v[36:39], v[166:169], v[190:193], v[36:39]
	v_mfma_f32_16x16x32_bf16 v[32:35], v[174:177], v[190:193], v[32:35]
	v_mfma_f32_16x16x32_bf16 v[20:23], v[166:169], v[198:201], v[20:23]
	v_mfma_f32_16x16x32_bf16 v[16:19], v[174:177], v[198:201], v[16:19]
	v_mfma_f32_16x16x32_bf16 v[4:7], v[166:169], v[206:209], v[4:7]
	v_mfma_f32_16x16x32_bf16 v[0:3], v[174:177], v[206:209], v[0:3]
	v_mfma_f32_16x16x32_bf16 v[52:55], v[170:173], v[186:189], v[52:55]
	v_mfma_f32_16x16x32_bf16 v[48:51], v[178:181], v[186:189], v[48:51]
	v_mfma_f32_16x16x32_bf16 v[36:39], v[170:173], v[194:197], v[36:39]
	v_mfma_f32_16x16x32_bf16 v[32:35], v[178:181], v[194:197], v[32:35]
	v_mfma_f32_16x16x32_bf16 v[20:23], v[170:173], v[202:205], v[20:23]
	v_mfma_f32_16x16x32_bf16 v[16:19], v[178:181], v[202:205], v[16:19]
	v_mfma_f32_16x16x32_bf16 v[4:7], v[170:173], v[210:213], v[4:7]
	v_mfma_f32_16x16x32_bf16 v[0:3], v[178:181], v[210:213], v[0:3]
	s_barrier
	s_add_i32 s56, s56, 2
	s_add_u32 s24, s24, 0x100
	s_addc_u32 s25, s25, 0
	s_add_u32 s54, s54, 0x100
	s_addc_u32 s55, s55, 0

; #define PG8_BAR __builtin_amdgcn_s_barrier()
; template <class Epi, class Sched, bool ALIGN_EPI = false, bool SP2 = false>
; __device__ __forceinline__ void gemm_phase(PG8_LAS unsigned char* lds, const Gemm g, const Sched& S, const Epi& E, int tid_in) {
;     ...
;         const bool has_next = S.next(ui + 1, nxt);
;         const char* nA = has_next ? (const char*)g.A + (size_t)nxt.pm * tstep : cA; const char* nB = has_next ? (const char*)g.Bt + (size_t)nxt.pn * tstep : cB;
;         for (int t = 0; t < nt; t += 2) {
;             if constexpr (Epi::MIDK) { if (t == Epi::MIDK_T) { if (wr == 0) PG8_BAR; E.mid(acc, cur, wr, wc, fr, fq); if (wr == 1) PG8_BAR; } }
;             const bool last = (t == nt - 2);
;             const char* a1 = cA + (size_t)(t + 1) * kstep;
;             const char* a2 = last ? nA : cA + (size_t)(t + 2) * kstep; const char* b2 = last ? nB : cB + (size_t)(t + 2) * kstep;
;             const char* a3 = a2 + kstep; const char* b3 = b2 + kstep;
;             if (last && has_next) S.a_ready(nxt);
;             if constexpr (SP2) {
;             PG8_LDB(B0, 0, 0); PG8_LDB(B1, 0, 1); PG8_SCHED; PG8_LDA(At, 0, 0); PG8_STAGE(PG8_SA(1, 1), a1 + hstep, voffA);
;             PG8_WAIT_V(8); PG8_WAIT_L(0); PG8_BAR; PG8_MMA(0, 0, At, B0); PG8_MMA(0, 1, At, B1); PG8_BAR; PG8_SCHED;
;             PG8_LDA(At, 0, 1); PG8_STAGE(PG8_SB(0, 0), b2, voffB); PG8_STAGE(PG8_SB(0, 1), b2 + hstep, voffB); PG8_STAGE(PG8_SA(0, 0), a2, voffA);
;             PG8_WAIT_V(8); PG8_WAIT_L(0); PG8_BAR; PG8_MMA(1, 0, At, B0); PG8_MMA(1, 1, At, B1); PG8_BAR; PG8_SCHED;
;             PG8_LDB(B0, 1, 0); PG8_LDB(B1, 1, 1); PG8_SCHED; PG8_LDA(At, 1, 0); PG8_STAGE(PG8_SA(0, 1), a2 + hstep, voffA);
;             PG8_WAIT_V(8); PG8_WAIT_L(0); PG8_BAR; PG8_MMA(0, 0, At, B0); PG8_MMA(0, 1, At, B1); PG8_BAR; PG8_SCHED;
;             PG8_LDA(At, 1, 1); PG8_STAGE(PG8_SB(1, 0), b3, voffB); PG8_STAGE(PG8_SB(1, 1), b3 + hstep, voffB); PG8_STAGE(PG8_SA(1, 0), a3, voffA);
;             PG8_WAIT_V(8); PG8_WAIT_L(0); PG8_BAR; PG8_MMA(1, 0, At, B0); PG8_MMA(1, 1, At, B1); PG8_BAR; PG8_SCHED;
;     ...
; #pragma unroll
;         for (int a = 0; a < 2; ++a)
; #pragma unroll
;             for (int b = 0; b < 2; ++b)
; #pragma unroll
;                 for (int m = 0; m < 4; ++m)
; #pragma unroll
;                     for (int n = 0; n < 2; ++n) acc[a][b][m][n] = (f32x4){0.f, 0.f, 0.f, 0.f};
.LBB0_460:
	s_add_u32 s12, s50, 0x100
	s_addc_u32 s75, s51, 0
	s_mov_b32 s76, -2
	s_waitcnt lgkmcnt(0)
	s_add_u32 s6, s48, 0x100
	s_addc_u32 s7, s49, 0
	s_cmp_eq_u32 s76, 40
	s_cselect_b32 s53, s45, s7
	s_cselect_b32 s52, s44, s6
	s_cselect_b32 s51, s47, s75
	s_cselect_b32 s50, s46, s12
	s_add_i32 m0, s60, 0xc000
	ds_read_b128 v[128:131], v236
	global_load_lds_dwordx4 v200, s[48:49]
	s_add_i32 m0, s60, 0xe000
	ds_read_b128 v[132:135], v236 offset:1024
	global_load_lds_dwordx4 v202, s[48:49]
	ds_read_b128 v[136:139], v236 offset:2048
	ds_read_b128 v[140:143], v236 offset:3072
	ds_read_b128 v[144:147], v237
	ds_read_b128 v[148:151], v237 offset:1024
	ds_read_b128 v[152:155], v237 offset:2048
	ds_read_b128 v[156:159], v237 offset:3072
	ds_read_b128 v[160:163], v238
	ds_read_b128 v[164:167], v238 offset:1024
	ds_read_b128 v[168:171], v238 offset:2048
	ds_read_b128 v[172:175], v238 offset:3072
	ds_read_b128 v[176:179], v238 offset:4096
	ds_read_b128 v[180:183], v238 offset:5120
	ds_read_b128 v[184:187], v238 offset:6144
	ds_read_b128 v[188:191], v238 offset:7168
	s_waitcnt vmcnt(8)
	s_waitcnt lgkmcnt(0)
	s_barrier
	v_mfma_f32_16x16x32_bf16 v[124:127], v[128:131], v[160:163], 0
	v_mfma_f32_16x16x32_bf16 v[120:123], v[136:139], v[160:163], 0
	v_mfma_f32_16x16x32_bf16 v[108:111], v[128:131], v[168:171], 0
	v_mfma_f32_16x16x32_bf16 v[104:107], v[136:139], v[168:171], 0
	v_mfma_f32_16x16x32_bf16 v[92:95], v[128:131], v[176:179], 0
	v_mfma_f32_16x16x32_bf16 v[88:91], v[136:139], v[176:179], 0
	v_mfma_f32_16x16x32_bf16 v[76:79], v[128:131], v[184:187], 0
	v_mfma_f32_16x16x32_bf16 v[72:75], v[136:139], v[184:187], 0
	v_mfma_f32_16x16x32_bf16 v[124:127], v[132:135], v[164:167], v[124:127]
	v_mfma_f32_16x16x32_bf16 v[120:123], v[140:143], v[164:167], v[120:123]
	v_mfma_f32_16x16x32_bf16 v[108:111], v[132:135], v[172:175], v[108:111]
	v_mfma_f32_16x16x32_bf16 v[104:107], v[140:143], v[172:175], v[104:107]
	v_mfma_f32_16x16x32_bf16 v[92:95], v[132:135], v[180:183], v[92:95]
	v_mfma_f32_16x16x32_bf16 v[88:91], v[140:143], v[180:183], v[88:91]
	v_mfma_f32_16x16x32_bf16 v[76:79], v[132:135], v[188:191], v[76:79]
	v_mfma_f32_16x16x32_bf16 v[72:75], v[140:143], v[188:191], v[72:75]
	v_mfma_f32_16x16x32_bf16 v[116:119], v[144:147], v[160:163], 0
	v_mfma_f32_16x16x32_bf16 v[112:115], v[152:155], v[160:163], 0
	v_mfma_f32_16x16x32_bf16 v[100:103], v[144:147], v[168:171], 0
	v_mfma_f32_16x16x32_bf16 v[96:99], v[152:155], v[168:171], 0
	v_mfma_f32_16x16x32_bf16 v[84:87], v[144:147], v[176:179], 0
	v_mfma_f32_16x16x32_bf16 v[80:83], v[152:155], v[176:179], 0
	v_mfma_f32_16x16x32_bf16 v[68:71], v[144:147], v[184:187], 0
	v_mfma_f32_16x16x32_bf16 v[64:67], v[152:155], v[184:187], 0
	v_mfma_f32_16x16x32_bf16 v[116:119], v[148:151], v[164:167], v[116:119]
	v_mfma_f32_16x16x32_bf16 v[112:115], v[156:159], v[164:167], v[112:115]
	v_mfma_f32_16x16x32_bf16 v[100:103], v[148:151], v[172:175], v[100:103]
	v_mfma_f32_16x16x32_bf16 v[96:99], v[156:159], v[172:175], v[96:99]
	v_mfma_f32_16x16x32_bf16 v[84:87], v[148:151], v[180:183], v[84:87]
	v_mfma_f32_16x16x32_bf16 v[80:83], v[156:159], v[180:183], v[80:83]
	v_mfma_f32_16x16x32_bf16 v[68:71], v[148:151], v[188:191], v[68:71]
	v_mfma_f32_16x16x32_bf16 v[64:67], v[156:159], v[188:191], v[64:67]
	s_barrier
	s_add_u32 s98, s50, s22
	s_addc_u32 s99, s51, s23
	s_add_u32 s100, s52, s22
	s_addc_u32 s101, s53, s23
	s_add_i32 s48, s70, s59
	s_mov_b32 m0, s48
	ds_read_b128 v[160:163], v238 offset:16384
	global_load_lds_dwordx4 v194, s[50:51]
	s_add_i32 m0, s48, 0x2000
	s_add_u32 s48, s50, 0xb0000
	s_addc_u32 s49, s51, 0
	s_add_i32 s77, s71, s59
	global_load_lds_dwordx4 v198, s[50:51]
	s_mov_b32 m0, s77
	ds_read_b128 v[164:167], v238 offset:17408
	global_load_lds_dwordx4 v194, s[48:49]
	s_add_i32 m0, s77, 0x2000
	ds_read_b128 v[168:171], v238 offset:18432
	global_load_lds_dwordx4 v198, s[48:49]
	s_mov_b32 m0, s60
	ds_read_b128 v[172:175], v238 offset:19456
	global_load_lds_dwordx4 v192, s[52:53]
	s_mov_b32 m0, s61
	ds_read_b128 v[176:179], v238 offset:20480
	global_load_lds_dwordx4 v196, s[52:53]
	ds_read_b128 v[180:183], v238 offset:21504
	ds_read_b128 v[184:187], v238 offset:22528
	ds_read_b128 v[188:191], v238 offset:23552
	s_waitcnt vmcnt(8)
	s_waitcnt lgkmcnt(0)
	s_barrier
	v_mfma_f32_16x16x32_bf16 v[60:63], v[128:131], v[160:163], 0
	v_mfma_f32_16x16x32_bf16 v[56:59], v[136:139], v[160:163], 0
	v_mfma_f32_16x16x32_bf16 v[44:47], v[128:131], v[168:171], 0
	v_mfma_f32_16x16x32_bf16 v[40:43], v[136:139], v[168:171], 0
	v_mfma_f32_16x16x32_bf16 v[28:31], v[128:131], v[176:179], 0
	v_mfma_f32_16x16x32_bf16 v[24:27], v[136:139], v[176:179], 0
	v_mfma_f32_16x16x32_bf16 v[12:15], v[128:131], v[184:187], 0
	v_mfma_f32_16x16x32_bf16 v[8:11], v[136:139], v[184:187], 0
	v_mfma_f32_16x16x32_bf16 v[60:63], v[132:135], v[164:167], v[60:63]
	v_mfma_f32_16x16x32_bf16 v[56:59], v[140:143], v[164:167], v[56:59]
	v_mfma_f32_16x16x32_bf16 v[44:47], v[132:135], v[172:175], v[44:47]
	v_mfma_f32_16x16x32_bf16 v[40:43], v[140:143], v[172:175], v[40:43]
	v_mfma_f32_16x16x32_bf16 v[28:31], v[132:135], v[180:183], v[28:31]
	v_mfma_f32_16x16x32_bf16 v[24:27], v[140:143], v[180:183], v[24:27]
	v_mfma_f32_16x16x32_bf16 v[12:15], v[132:135], v[188:191], v[12:15]
	v_mfma_f32_16x16x32_bf16 v[8:11], v[140:143], v[188:191], v[8:11]
	v_mfma_f32_16x16x32_bf16 v[52:55], v[144:147], v[160:163], 0
	v_mfma_f32_16x16x32_bf16 v[48:51], v[152:155], v[160:163], 0
	v_mfma_f32_16x16x32_bf16 v[36:39], v[144:147], v[168:171], 0
	v_mfma_f32_16x16x32_bf16 v[32:35], v[152:155], v[168:171], 0
	v_mfma_f32_16x16x32_bf16 v[20:23], v[144:147], v[176:179], 0
	v_mfma_f32_16x16x32_bf16 v[16:19], v[152:155], v[176:179], 0
	v_mfma_f32_16x16x32_bf16 v[4:7], v[144:147], v[184:187], 0
	v_mfma_f32_16x16x32_bf16 v[0:3], v[152:155], v[184:187], 0
	v_mfma_f32_16x16x32_bf16 v[52:55], v[148:151], v[164:167], v[52:55]
	v_mfma_f32_16x16x32_bf16 v[48:51], v[156:159], v[164:167], v[48:51]
	v_mfma_f32_16x16x32_bf16 v[36:39], v[148:151], v[172:175], v[36:39]
	v_mfma_f32_16x16x32_bf16 v[32:35], v[156:159], v[172:175], v[32:35]
	v_mfma_f32_16x16x32_bf16 v[20:23], v[148:151], v[180:183], v[20:23]
	v_mfma_f32_16x16x32_bf16 v[16:19], v[156:159], v[180:183], v[16:19]
	v_mfma_f32_16x16x32_bf16 v[4:7], v[148:151], v[188:191], v[4:7]
	v_mfma_f32_16x16x32_bf16 v[0:3], v[156:159], v[188:191], v[0:3]
	s_barrier
; #define PG8_STAGE(bufoff, gbase, voff) do { _Pragma("unroll") for (int _i = 0; _i < 2; ++_i) \
;         __builtin_amdgcn_global_load_lds((const unsigned*)((const char*)(gbase) + (voff)[_i]), (PG8_LAS unsigned*)(lds + (bufoff) + ldsw + _i * 8192), 16, 0, 0); } while (0)
; #define PG8_LDA(dst, b, h) do { _Pragma("unroll") for (int m = 0; m < 4; ++m) _Pragma("unroll") for (int k = 0; k < 2; ++k) dst[m][k] = *(const PG8_LAS bf16x8*)(lds + PG8_SA(b, h) + aoff + m * 2048 + k * 1024); } while (0)
; #define PG8_LDB(dst, b, h) do { _Pragma("unroll") for (int n = 0; n < 2; ++n) _Pragma("unroll") for (int k = 0; k < 2; ++k) dst[n][k] = *(const PG8_LAS bf16x8*)(lds + PG8_SB(b, h) + boff + n * 2048 + k * 1024); } while (0)
; #define PG8_MMA(ai, bj, At, Bt) do { __builtin_amdgcn_s_setprio(1); _Pragma("unroll") for (int m = 0; m < 4; ++m) _Pragma("unroll") for (int n = 0; n < 2; ++n) _Pragma("unroll") for (int k = 0; k < 2; ++k) \
;         acc[ai][bj][m][n] = __builtin_amdgcn_mfma_f32_16x16x32_bf16(Bt[n][k], At[m][k], acc[ai][bj][m][n], 0, 0, 0); __builtin_amdgcn_s_setprio(0); } while (0)
; #define PG8_WAIT_V(n) asm volatile("s_waitcnt vmcnt(" #n ")" ::: "memory")
; #define PG8_WAIT_L(n) asm volatile("s_waitcnt lgkmcnt(" #n ")" ::: "memory")
; #define PG8_BAR __builtin_amdgcn_s_barrier()
; #define PG8_SCHED __builtin_amdgcn_sched_barrier(0)
; template <class Epi, class Sched, bool ALIGN_EPI = false, bool SP2 = false>
; __device__ __forceinline__ void gemm_phase(PG8_LAS unsigned char* lds, const Gemm g, const Sched& S, const Epi& E, int tid_in) {
;     ...
;             PG8_LDB(B0, 1, 0); PG8_LDB(B1, 1, 1); PG8_SCHED; PG8_LDA(At, 1, 0); PG8_STAGE(PG8_SA(0, 1), a2 + hstep, voffA);
;             PG8_WAIT_V(8); PG8_WAIT_L(0); PG8_BAR; PG8_MMA(0, 0, At, B0); PG8_MMA(0, 1, At, B1); PG8_BAR; PG8_SCHED;
;             PG8_LDA(At, 1, 1); PG8_STAGE(PG8_SB(1, 0), b3, voffB); PG8_STAGE(PG8_SB(1, 1), b3 + hstep, voffB); PG8_STAGE(PG8_SA(1, 0), a3, voffA);
;             PG8_WAIT_V(8); PG8_WAIT_L(0); PG8_BAR; PG8_MMA(1, 0, At, B0); PG8_MMA(1, 1, At, B1); PG8_BAR; PG8_SCHED;
	s_add_i32 s77, 0, 0x18000
	s_add_i32 s78, 0, 0x1c000
	s_add_u32 s48, s52, 0xb0000
	s_addc_u32 s49, s53, 0
	s_mov_b32 m0, s62
	s_nop 0
	global_load_lds_dwordx4 v192, s[48:49]
	s_mov_b32 m0, s63
	s_nop 0
	global_load_lds_dwordx4 v196, s[48:49]
	v_add_u32_e32 v140, s77, v232
	v_add_u32_e32 v156, s78, v232
	ds_read_b128 v[128:131], v140
	ds_read_b128 v[132:135], v140 offset:1024
	ds_read_b128 v[136:139], v140 offset:2048
	ds_read_b128 v[140:143], v140 offset:3072
	ds_read_b128 v[144:147], v156
	ds_read_b128 v[148:151], v156 offset:1024
	ds_read_b128 v[152:155], v156 offset:2048
	ds_read_b128 v[156:159], v156 offset:3072
	ds_read_b128 v[160:163], v238 offset:32768
	ds_read_b128 v[164:167], v238 offset:33792
	ds_read_b128 v[168:171], v238 offset:34816
	ds_read_b128 v[172:175], v238 offset:35840
	ds_read_b128 v[176:179], v238 offset:36864
	ds_read_b128 v[180:183], v238 offset:37888
	ds_read_b128 v[184:187], v238 offset:38912
	ds_read_b128 v[188:191], v238 offset:39936
	s_waitcnt vmcnt(8)
	s_waitcnt lgkmcnt(0)
	s_barrier
	v_mfma_f32_16x16x32_bf16 v[124:127], v[128:131], v[160:163], v[124:127]
	v_mfma_f32_16x16x32_bf16 v[120:123], v[136:139], v[160:163], v[120:123]
	v_mfma_f32_16x16x32_bf16 v[108:111], v[128:131], v[168:171], v[108:111]
	v_mfma_f32_16x16x32_bf16 v[104:107], v[136:139], v[168:171], v[104:107]
	v_mfma_f32_16x16x32_bf16 v[92:95], v[128:131], v[176:179], v[92:95]
	v_mfma_f32_16x16x32_bf16 v[88:91], v[136:139], v[176:179], v[88:91]
	v_mfma_f32_16x16x32_bf16 v[76:79], v[128:131], v[184:187], v[76:79]
	v_mfma_f32_16x16x32_bf16 v[72:75], v[136:139], v[184:187], v[72:75]
	v_mfma_f32_16x16x32_bf16 v[124:127], v[132:135], v[164:167], v[124:127]
	v_mfma_f32_16x16x32_bf16 v[120:123], v[140:143], v[164:167], v[120:123]
	v_mfma_f32_16x16x32_bf16 v[108:111], v[132:135], v[172:175], v[108:111]
	v_mfma_f32_16x16x32_bf16 v[104:107], v[140:143], v[172:175], v[104:107]
	v_mfma_f32_16x16x32_bf16 v[92:95], v[132:135], v[180:183], v[92:95]
	v_mfma_f32_16x16x32_bf16 v[88:91], v[140:143], v[180:183], v[88:91]
	v_mfma_f32_16x16x32_bf16 v[76:79], v[132:135], v[188:191], v[76:79]
	v_mfma_f32_16x16x32_bf16 v[72:75], v[140:143], v[188:191], v[72:75]
	v_mfma_f32_16x16x32_bf16 v[116:119], v[144:147], v[160:163], v[116:119]
	v_mfma_f32_16x16x32_bf16 v[112:115], v[152:155], v[160:163], v[112:115]
	v_mfma_f32_16x16x32_bf16 v[100:103], v[144:147], v[168:171], v[100:103]
	v_mfma_f32_16x16x32_bf16 v[96:99], v[152:155], v[168:171], v[96:99]
	v_mfma_f32_16x16x32_bf16 v[84:87], v[144:147], v[176:179], v[84:87]
	v_mfma_f32_16x16x32_bf16 v[80:83], v[152:155], v[176:179], v[80:83]
	v_mfma_f32_16x16x32_bf16 v[68:71], v[144:147], v[184:187], v[68:71]
	v_mfma_f32_16x16x32_bf16 v[64:67], v[152:155], v[184:187], v[64:67]
	v_mfma_f32_16x16x32_bf16 v[116:119], v[148:151], v[164:167], v[116:119]
	v_mfma_f32_16x16x32_bf16 v[112:115], v[156:159], v[164:167], v[112:115]
	v_mfma_f32_16x16x32_bf16 v[100:103], v[148:151], v[172:175], v[100:103]
	v_mfma_f32_16x16x32_bf16 v[96:99], v[156:159], v[172:175], v[96:99]
	v_mfma_f32_16x16x32_bf16 v[84:87], v[148:151], v[180:183], v[84:87]
	v_mfma_f32_16x16x32_bf16 v[80:83], v[156:159], v[180:183], v[80:83]
	v_mfma_f32_16x16x32_bf16 v[68:71], v[148:151], v[188:191], v[68:71]
	v_mfma_f32_16x16x32_bf16 v[64:67], v[156:159], v[188:191], v[64:67]
	s_barrier
	s_add_i32 s48, s77, s59
	s_mov_b32 m0, s48
	ds_read_b128 v[160:163], v238 offset:49152
	global_load_lds_dwordx4 v194, s[98:99]
	s_add_i32 m0, s48, 0x2000
	s_add_u32 s48, s50, 0xb0080
	s_addc_u32 s49, s51, 0
	s_add_i32 s50, s78, s59
	global_load_lds_dwordx4 v198, s[98:99]
	s_mov_b32 m0, s50
	ds_read_b128 v[164:167], v238 offset:50176
	global_load_lds_dwordx4 v194, s[48:49]
	s_add_i32 m0, s50, 0x2000
	ds_read_b128 v[168:171], v238 offset:51200
	global_load_lds_dwordx4 v198, s[48:49]
	s_mov_b32 m0, s65
	ds_read_b128 v[172:175], v238 offset:52224
	global_load_lds_dwordx4 v192, s[100:101]
	s_mov_b32 m0, s67
	ds_read_b128 v[176:179], v238 offset:53248
	global_load_lds_dwordx4 v196, s[100:101]
	ds_read_b128 v[180:183], v238 offset:54272
	ds_read_b128 v[184:187], v238 offset:55296
	ds_read_b128 v[188:191], v238 offset:56320
	s_waitcnt vmcnt(8)
	s_waitcnt lgkmcnt(0)
	s_barrier
	v_mfma_f32_16x16x32_bf16 v[60:63], v[128:131], v[160:163], v[60:63]
	v_mfma_f32_16x16x32_bf16 v[56:59], v[136:139], v[160:163], v[56:59]
	v_mfma_f32_16x16x32_bf16 v[44:47], v[128:131], v[168:171], v[44:47]
	v_mfma_f32_16x16x32_bf16 v[40:43], v[136:139], v[168:171], v[40:43]
	v_mfma_f32_16x16x32_bf16 v[28:31], v[128:131], v[176:179], v[28:31]
	v_mfma_f32_16x16x32_bf16 v[24:27], v[136:139], v[176:179], v[24:27]
	v_mfma_f32_16x16x32_bf16 v[12:15], v[128:131], v[184:187], v[12:15]
	v_mfma_f32_16x16x32_bf16 v[8:11], v[136:139], v[184:187], v[8:11]
	v_mfma_f32_16x16x32_bf16 v[60:63], v[132:135], v[164:167], v[60:63]
	v_mfma_f32_16x16x32_bf16 v[56:59], v[140:143], v[164:167], v[56:59]
	v_mfma_f32_16x16x32_bf16 v[44:47], v[132:135], v[172:175], v[44:47]
	v_mfma_f32_16x16x32_bf16 v[40:43], v[140:143], v[172:175], v[40:43]
	v_mfma_f32_16x16x32_bf16 v[28:31], v[132:135], v[180:183], v[28:31]
	v_mfma_f32_16x16x32_bf16 v[24:27], v[140:143], v[180:183], v[24:27]
	v_mfma_f32_16x16x32_bf16 v[12:15], v[132:135], v[188:191], v[12:15]
	v_mfma_f32_16x16x32_bf16 v[8:11], v[140:143], v[188:191], v[8:11]
	v_mfma_f32_16x16x32_bf16 v[52:55], v[144:147], v[160:163], v[52:55]
	v_mfma_f32_16x16x32_bf16 v[48:51], v[152:155], v[160:163], v[48:51]
	v_mfma_f32_16x16x32_bf16 v[36:39], v[144:147], v[168:171], v[36:39]
	v_mfma_f32_16x16x32_bf16 v[32:35], v[152:155], v[168:171], v[32:35]
	v_mfma_f32_16x16x32_bf16 v[20:23], v[144:147], v[176:179], v[20:23]
	v_mfma_f32_16x16x32_bf16 v[16:19], v[152:155], v[176:179], v[16:19]
	v_mfma_f32_16x16x32_bf16 v[4:7], v[144:147], v[184:187], v[4:7]
	v_mfma_f32_16x16x32_bf16 v[0:3], v[152:155], v[184:187], v[0:3]
	v_mfma_f32_16x16x32_bf16 v[52:55], v[148:151], v[164:167], v[52:55]
	v_mfma_f32_16x16x32_bf16 v[48:51], v[156:159], v[164:167], v[48:51]
	v_mfma_f32_16x16x32_bf16 v[36:39], v[148:151], v[172:175], v[36:39]
	v_mfma_f32_16x16x32_bf16 v[32:35], v[156:159], v[172:175], v[32:35]
	v_mfma_f32_16x16x32_bf16 v[20:23], v[148:151], v[180:183], v[20:23]
	v_mfma_f32_16x16x32_bf16 v[16:19], v[156:159], v[180:183], v[16:19]
	v_mfma_f32_16x16x32_bf16 v[4:7], v[148:151], v[188:191], v[4:7]
	v_mfma_f32_16x16x32_bf16 v[0:3], v[156:159], v[188:191], v[0:3]
	s_barrier
	s_add_i32 s76, s76, 2
	s_add_u32 s12, s12, 0x100
	s_addc_u32 s75, s75, 0
	s_mov_b64 s[48:49], s[6:7]

; #define PG8_STAGE(bufoff, gbase, voff) do { _Pragma("unroll") for (int _i = 0; _i < 2; ++_i) \
;         __builtin_amdgcn_global_load_lds((const unsigned*)((const char*)(gbase) + (voff)[_i]), (PG8_LAS unsigned*)(lds + (bufoff) + ldsw + _i * 8192), 16, 0, 0); } while (0)
; #define PG8_LDA(dst, b, h) do { _Pragma("unroll") for (int m = 0; m < 4; ++m) _Pragma("unroll") for (int k = 0; k < 2; ++k) dst[m][k] = *(const PG8_LAS bf16x8*)(lds + PG8_SA(b, h) + aoff + m * 2048 + k * 1024); } while (0)
; #define PG8_WAIT_V(n) asm volatile("s_waitcnt vmcnt(" #n ")" ::: "memory")
; template <class Epi, class Sched, bool ALIGN_EPI = false, bool SP2 = false>
; __device__ __forceinline__ void gemm_phase(PG8_LAS unsigned char* lds, const Gemm g, const Sched& S, const Epi& E, int tid_in) {
;     ...
;         const bool has_next = S.next(ui + 1, nxt);
;         const char* nA = has_next ? (const char*)g.A + (size_t)nxt.pm * tstep : cA; const char* nB = has_next ? (const char*)g.Bt + (size_t)nxt.pn * tstep : cB;
;         for (int t = 0; t < nt; t += 2) {
;             if constexpr (Epi::MIDK) { if (t == Epi::MIDK_T) { if (wr == 0) PG8_BAR; E.mid(acc, cur, wr, wc, fr, fq); if (wr == 1) PG8_BAR; } }
;             const bool last = (t == nt - 2);
;             const char* a1 = cA + (size_t)(t + 1) * kstep;
;             const char* a2 = last ? nA : cA + (size_t)(t + 2) * kstep; const char* b2 = last ? nB : cB + (size_t)(t + 2) * kstep;
;             const char* a3 = a2 + kstep; const char* b3 = b2 + kstep;
;             if (last && has_next) S.a_ready(nxt);
;             if constexpr (SP2) {
;             PG8_LDB(B0, 0, 0); PG8_LDB(B1, 0, 1); PG8_SCHED; PG8_LDA(At, 0, 0); PG8_STAGE(PG8_SA(1, 1), a1 + hstep, voffA);
;             PG8_WAIT_V(8); PG8_WAIT_L(0); PG8_BAR; PG8_MMA(0, 0, At, B0); PG8_MMA(0, 1, At, B1); PG8_BAR; PG8_SCHED;
;             PG8_LDA(At, 0, 1); PG8_STAGE(PG8_SB(0, 0), b2, voffB); PG8_STAGE(PG8_SB(0, 1), b2 + hstep, voffB); PG8_STAGE(PG8_SA(0, 0), a2, voffA);
;             PG8_WAIT_V(8); PG8_WAIT_L(0); PG8_BAR; PG8_MMA(1, 0, At, B0); PG8_MMA(1, 1, At, B1); PG8_BAR; PG8_SCHED;
;     ...
; #pragma unroll
;         for (int a = 0; a < 2; ++a)
; #pragma unroll
;             for (int b = 0; b < 2; ++b)
; #pragma unroll
;                 for (int m = 0; m < 4; ++m)
; #pragma unroll
;                     for (int n = 0; n < 2; ++n) acc[a][b][m][n] = (f32x4){0.f, 0.f, 0.f, 0.f};
.LBB0_563:
	s_ashr_i32 s35, s34, 31
	s_lshl_b64 s[0:1], s[34:35], 19
	s_add_u32 s36, s54, s0
	s_addc_u32 s37, s55, s1
	s_and_b64 s[0:1], s[4:5], exec
	s_cselect_b32 s0, s37, s47
	s_cselect_b32 s1, s36, s46
	s_ashr_i32 s31, s30, 31
	s_lshl_b64 s[38:39], s[30:31], 19
	s_add_u32 s38, s56, s38
	s_addc_u32 s39, s57, s39
	s_and_b64 s[50:51], s[4:5], exec
	s_cselect_b32 s7, s39, s49
	s_cselect_b32 s31, s38, s48
	s_add_u32 s46, s46, 0x40080
	s_addc_u32 s47, s47, 0
	s_add_u32 s35, s48, 0x100
	s_addc_u32 s45, s49, 0
	s_mov_b32 s52, -2
	s_add_u32 s48, s46, 0xfffc0080
	s_addc_u32 s49, s47, -1
	s_cmp_eq_u32 s52, 12
	s_cselect_b32 s51, s0, s49
	s_cselect_b32 s50, s1, s48
	s_cselect_b32 s49, s7, s45
	s_cselect_b32 s48, s31, s35
	s_add_i32 m0, s59, 0xc000
	ds_read_b128 v[128:131], v180
	global_load_lds_dwordx4 v158, s[46:47]
	s_add_i32 m0, s59, 0xe000
	ds_read_b128 v[132:135], v180 offset:1024
	global_load_lds_dwordx4 v160, s[46:47]
	ds_read_b128 v[136:139], v180 offset:2048
	ds_read_b128 v[140:143], v180 offset:3072
	ds_read_b128 v[166:169], v181
	ds_read_b128 v[170:173], v181 offset:1024
	ds_read_b128 v[174:177], v181 offset:2048
	ds_read_b128 v[184:187], v181 offset:3072
	ds_read_b128 v[188:191], v182
	ds_read_b128 v[192:195], v182 offset:1024
	ds_read_b128 v[196:199], v182 offset:2048
	ds_read_b128 v[200:203], v182 offset:3072
	ds_read_b128 v[204:207], v182 offset:4096
	ds_read_b128 v[208:211], v182 offset:5120
	ds_read_b128 v[212:215], v182 offset:6144
	ds_read_b128 v[216:219], v182 offset:7168
	s_waitcnt vmcnt(8)
	s_waitcnt lgkmcnt(0)
	s_barrier
	v_mfma_f32_16x16x32_bf16 v[68:71], v[128:131], v[188:191], 0
	v_mfma_f32_16x16x32_bf16 v[56:59], v[136:139], v[188:191], 0
	v_mfma_f32_16x16x32_bf16 v[52:55], v[128:131], v[196:199], 0
	v_mfma_f32_16x16x32_bf16 v[48:51], v[136:139], v[196:199], 0
	v_mfma_f32_16x16x32_bf16 v[44:47], v[128:131], v[204:207], 0
	v_mfma_f32_16x16x32_bf16 v[40:43], v[136:139], v[204:207], 0
	v_mfma_f32_16x16x32_bf16 v[36:39], v[128:131], v[212:215], 0
	v_mfma_f32_16x16x32_bf16 v[32:35], v[136:139], v[212:215], 0
	v_mfma_f32_16x16x32_bf16 v[68:71], v[132:135], v[192:195], v[68:71]
	v_mfma_f32_16x16x32_bf16 v[56:59], v[140:143], v[192:195], v[56:59]
	v_mfma_f32_16x16x32_bf16 v[52:55], v[132:135], v[200:203], v[52:55]
	v_mfma_f32_16x16x32_bf16 v[48:51], v[140:143], v[200:203], v[48:51]
	v_mfma_f32_16x16x32_bf16 v[44:47], v[132:135], v[208:211], v[44:47]
	v_mfma_f32_16x16x32_bf16 v[40:43], v[140:143], v[208:211], v[40:43]
	v_mfma_f32_16x16x32_bf16 v[36:39], v[132:135], v[216:219], v[36:39]
	v_mfma_f32_16x16x32_bf16 v[32:35], v[140:143], v[216:219], v[32:35]
	v_mfma_f32_16x16x32_bf16 v[124:127], v[166:169], v[188:191], 0
	v_mfma_f32_16x16x32_bf16 v[120:123], v[174:177], v[188:191], 0
	v_mfma_f32_16x16x32_bf16 v[116:119], v[166:169], v[196:199], 0
	v_mfma_f32_16x16x32_bf16 v[112:115], v[174:177], v[196:199], 0
	v_mfma_f32_16x16x32_bf16 v[108:111], v[166:169], v[204:207], 0
	v_mfma_f32_16x16x32_bf16 v[104:107], v[174:177], v[204:207], 0
	v_mfma_f32_16x16x32_bf16 v[100:103], v[166:169], v[212:215], 0
	v_mfma_f32_16x16x32_bf16 v[96:99], v[174:177], v[212:215], 0
	v_mfma_f32_16x16x32_bf16 v[124:127], v[170:173], v[192:195], v[124:127]
	v_mfma_f32_16x16x32_bf16 v[120:123], v[184:187], v[192:195], v[120:123]
	v_mfma_f32_16x16x32_bf16 v[116:119], v[170:173], v[200:203], v[116:119]
	v_mfma_f32_16x16x32_bf16 v[112:115], v[184:187], v[200:203], v[112:115]
	v_mfma_f32_16x16x32_bf16 v[108:111], v[170:173], v[208:211], v[108:111]
	v_mfma_f32_16x16x32_bf16 v[104:107], v[184:187], v[208:211], v[104:107]
	v_mfma_f32_16x16x32_bf16 v[100:103], v[170:173], v[216:219], v[100:103]
	v_mfma_f32_16x16x32_bf16 v[96:99], v[184:187], v[216:219], v[96:99]
	s_barrier
	s_add_u32 s98, s48, s14
	s_addc_u32 s99, s49, s15
	s_add_u32 s100, s50, s14
	s_addc_u32 s101, s51, s15
	s_add_i32 s53, s77, s29
	s_mov_b32 m0, s53
	ds_read_b128 v[188:191], v182 offset:16384
	global_load_lds_dwordx4 v146, s[48:49]
	s_add_i32 m0, s53, 0x2000
	s_add_u32 s88, s48, 0x40000
	s_addc_u32 s89, s49, 0
	s_add_i32 s53, s78, s29
	global_load_lds_dwordx4 v150, s[48:49]
	s_mov_b32 m0, s53
	ds_read_b128 v[192:195], v182 offset:17408
	global_load_lds_dwordx4 v146, s[88:89]
	s_add_i32 m0, s53, 0x2000
	ds_read_b128 v[196:199], v182 offset:18432
	global_load_lds_dwordx4 v150, s[88:89]
	s_mov_b32 m0, s59
	ds_read_b128 v[200:203], v182 offset:19456
	global_load_lds_dwordx4 v144, s[50:51]
	s_mov_b32 m0, s60
	ds_read_b128 v[204:207], v182 offset:20480
	global_load_lds_dwordx4 v148, s[50:51]
	ds_read_b128 v[208:211], v182 offset:21504
	ds_read_b128 v[212:215], v182 offset:22528
	ds_read_b128 v[216:219], v182 offset:23552
	s_waitcnt vmcnt(8)
	s_waitcnt lgkmcnt(0)
	s_barrier
; #define PG8_STAGE(bufoff, gbase, voff) do { _Pragma("unroll") for (int _i = 0; _i < 2; ++_i) \
;         __builtin_amdgcn_global_load_lds((const unsigned*)((const char*)(gbase) + (voff)[_i]), (PG8_LAS unsigned*)(lds + (bufoff) + ldsw + _i * 8192), 16, 0, 0); } while (0)
; #define PG8_LDA(dst, b, h) do { _Pragma("unroll") for (int m = 0; m < 4; ++m) _Pragma("unroll") for (int k = 0; k < 2; ++k) dst[m][k] = *(const PG8_LAS bf16x8*)(lds + PG8_SA(b, h) + aoff + m * 2048 + k * 1024); } while (0)
; #define PG8_LDB(dst, b, h) do { _Pragma("unroll") for (int n = 0; n < 2; ++n) _Pragma("unroll") for (int k = 0; k < 2; ++k) dst[n][k] = *(const PG8_LAS bf16x8*)(lds + PG8_SB(b, h) + boff + n * 2048 + k * 1024); } while (0)
; #define PG8_MMA(ai, bj, At, Bt) do { __builtin_amdgcn_s_setprio(1); _Pragma("unroll") for (int m = 0; m < 4; ++m) _Pragma("unroll") for (int n = 0; n < 2; ++n) _Pragma("unroll") for (int k = 0; k < 2; ++k) \
;         acc[ai][bj][m][n] = __builtin_amdgcn_mfma_f32_16x16x32_bf16(Bt[n][k], At[m][k], acc[ai][bj][m][n], 0, 0, 0); __builtin_amdgcn_s_setprio(0); } while (0)
; #define PG8_WAIT_V(n) asm volatile("s_waitcnt vmcnt(" #n ")" ::: "memory")
; #define PG8_WAIT_L(n) asm volatile("s_waitcnt lgkmcnt(" #n ")" ::: "memory")
; template <class Epi, class Sched, bool ALIGN_EPI = false, bool SP2 = false>
; __device__ __forceinline__ void gemm_phase(PG8_LAS unsigned char* lds, const Gemm g, const Sched& S, const Epi& E, int tid_in) {
;     ...
;             PG8_WAIT_V(8); PG8_WAIT_L(0); PG8_BAR; PG8_MMA(0, 0, At, B0); PG8_MMA(0, 1, At, B1); PG8_BAR; PG8_SCHED;
;             PG8_LDA(At, 0, 1); PG8_STAGE(PG8_SB(0, 0), b2, voffB); PG8_STAGE(PG8_SB(0, 1), b2 + hstep, voffB); PG8_STAGE(PG8_SA(0, 0), a2, voffA);
;             PG8_WAIT_V(8); PG8_WAIT_L(0); PG8_BAR; PG8_MMA(1, 0, At, B0); PG8_MMA(1, 1, At, B1); PG8_BAR; PG8_SCHED;
;             PG8_LDB(B0, 1, 0); PG8_LDB(B1, 1, 1); PG8_SCHED; PG8_LDA(At, 1, 0); PG8_STAGE(PG8_SA(0, 1), a2 + hstep, voffA);
;             PG8_WAIT_V(8); PG8_WAIT_L(0); PG8_BAR; PG8_MMA(0, 0, At, B0); PG8_MMA(0, 1, At, B1); PG8_BAR; PG8_SCHED;
;             PG8_LDA(At, 1, 1); PG8_STAGE(PG8_SB(1, 0), b3, voffB); PG8_STAGE(PG8_SB(1, 1), b3 + hstep, voffB); PG8_STAGE(PG8_SA(1, 0), a3, voffA);
;             PG8_WAIT_V(8); PG8_WAIT_L(0); PG8_BAR; PG8_MMA(1, 0, At, B0); PG8_MMA(1, 1, At, B1); PG8_BAR; PG8_SCHED;
	v_mfma_f32_16x16x32_bf16 v[28:31], v[128:131], v[188:191], 0
	v_mfma_f32_16x16x32_bf16 v[24:27], v[136:139], v[188:191], 0
	v_mfma_f32_16x16x32_bf16 v[20:23], v[128:131], v[196:199], 0
	v_mfma_f32_16x16x32_bf16 v[16:19], v[136:139], v[196:199], 0
	v_mfma_f32_16x16x32_bf16 v[12:15], v[128:131], v[204:207], 0
	v_mfma_f32_16x16x32_bf16 v[8:11], v[136:139], v[204:207], 0
	v_mfma_f32_16x16x32_bf16 v[4:7], v[128:131], v[212:215], 0
	v_mfma_f32_16x16x32_bf16 v[0:3], v[136:139], v[212:215], 0
	v_mfma_f32_16x16x32_bf16 v[28:31], v[132:135], v[192:195], v[28:31]
	v_mfma_f32_16x16x32_bf16 v[24:27], v[140:143], v[192:195], v[24:27]
	v_mfma_f32_16x16x32_bf16 v[20:23], v[132:135], v[200:203], v[20:23]
	v_mfma_f32_16x16x32_bf16 v[16:19], v[140:143], v[200:203], v[16:19]
	v_mfma_f32_16x16x32_bf16 v[12:15], v[132:135], v[208:211], v[12:15]
	v_mfma_f32_16x16x32_bf16 v[8:11], v[140:143], v[208:211], v[8:11]
	v_mfma_f32_16x16x32_bf16 v[4:7], v[132:135], v[216:219], v[4:7]
	v_mfma_f32_16x16x32_bf16 v[0:3], v[140:143], v[216:219], v[0:3]
	v_mfma_f32_16x16x32_bf16 v[92:95], v[166:169], v[188:191], 0
	v_mfma_f32_16x16x32_bf16 v[88:91], v[174:177], v[188:191], 0
	v_mfma_f32_16x16x32_bf16 v[84:87], v[166:169], v[196:199], 0
	v_mfma_f32_16x16x32_bf16 v[80:83], v[174:177], v[196:199], 0
	v_mfma_f32_16x16x32_bf16 v[76:79], v[166:169], v[204:207], 0
	v_mfma_f32_16x16x32_bf16 v[72:75], v[174:177], v[204:207], 0
	v_mfma_f32_16x16x32_bf16 v[64:67], v[166:169], v[212:215], 0
	v_mfma_f32_16x16x32_bf16 v[60:63], v[174:177], v[212:215], 0
	v_mfma_f32_16x16x32_bf16 v[92:95], v[170:173], v[192:195], v[92:95]
	v_mfma_f32_16x16x32_bf16 v[88:91], v[184:187], v[192:195], v[88:91]
	v_mfma_f32_16x16x32_bf16 v[84:87], v[170:173], v[200:203], v[84:87]
	v_mfma_f32_16x16x32_bf16 v[80:83], v[184:187], v[200:203], v[80:83]
	v_mfma_f32_16x16x32_bf16 v[76:79], v[170:173], v[208:211], v[76:79]
	v_mfma_f32_16x16x32_bf16 v[72:75], v[184:187], v[208:211], v[72:75]
	v_mfma_f32_16x16x32_bf16 v[64:67], v[170:173], v[216:219], v[64:67]
	v_mfma_f32_16x16x32_bf16 v[60:63], v[184:187], v[216:219], v[60:63]
	s_barrier
	s_add_i32 s53, 0, 0x18000
	s_add_i32 s88, 0, 0x1c000
	s_add_u32 s50, s50, 0x40000
	s_addc_u32 s51, s51, 0
	s_mov_b32 m0, s61
	s_nop 0
	global_load_lds_dwordx4 v144, s[50:51]
	s_mov_b32 m0, s62
	s_nop 0
	global_load_lds_dwordx4 v148, s[50:51]
	v_add_u32_e32 v140, s53, v179
	v_add_u32_e32 v184, s88, v179
	ds_read_b128 v[128:131], v140
	ds_read_b128 v[132:135], v140 offset:1024
	ds_read_b128 v[136:139], v140 offset:2048
	ds_read_b128 v[140:143], v140 offset:3072
	ds_read_b128 v[166:169], v184
	ds_read_b128 v[170:173], v184 offset:1024
	ds_read_b128 v[174:177], v184 offset:2048
	ds_read_b128 v[184:187], v184 offset:3072
	ds_read_b128 v[188:191], v182 offset:32768
	ds_read_b128 v[192:195], v182 offset:33792
	ds_read_b128 v[196:199], v182 offset:34816
	ds_read_b128 v[200:203], v182 offset:35840
	ds_read_b128 v[204:207], v182 offset:36864
	ds_read_b128 v[208:211], v182 offset:37888
	ds_read_b128 v[212:215], v182 offset:38912
	ds_read_b128 v[216:219], v182 offset:39936
	s_waitcnt vmcnt(8)
	s_waitcnt lgkmcnt(0)
	s_barrier
	v_mfma_f32_16x16x32_bf16 v[68:71], v[128:131], v[188:191], v[68:71]
	v_mfma_f32_16x16x32_bf16 v[56:59], v[136:139], v[188:191], v[56:59]
	v_mfma_f32_16x16x32_bf16 v[52:55], v[128:131], v[196:199], v[52:55]
	v_mfma_f32_16x16x32_bf16 v[48:51], v[136:139], v[196:199], v[48:51]
	v_mfma_f32_16x16x32_bf16 v[44:47], v[128:131], v[204:207], v[44:47]
	v_mfma_f32_16x16x32_bf16 v[40:43], v[136:139], v[204:207], v[40:43]
	v_mfma_f32_16x16x32_bf16 v[36:39], v[128:131], v[212:215], v[36:39]
	v_mfma_f32_16x16x32_bf16 v[32:35], v[136:139], v[212:215], v[32:35]
	v_mfma_f32_16x16x32_bf16 v[68:71], v[132:135], v[192:195], v[68:71]
	v_mfma_f32_16x16x32_bf16 v[56:59], v[140:143], v[192:195], v[56:59]
	v_mfma_f32_16x16x32_bf16 v[52:55], v[132:135], v[200:203], v[52:55]
	v_mfma_f32_16x16x32_bf16 v[48:51], v[140:143], v[200:203], v[48:51]
	v_mfma_f32_16x16x32_bf16 v[44:47], v[132:135], v[208:211], v[44:47]
	v_mfma_f32_16x16x32_bf16 v[40:43], v[140:143], v[208:211], v[40:43]
	v_mfma_f32_16x16x32_bf16 v[36:39], v[132:135], v[216:219], v[36:39]
	v_mfma_f32_16x16x32_bf16 v[32:35], v[140:143], v[216:219], v[32:35]
	v_mfma_f32_16x16x32_bf16 v[124:127], v[166:169], v[188:191], v[124:127]
	v_mfma_f32_16x16x32_bf16 v[120:123], v[174:177], v[188:191], v[120:123]
	v_mfma_f32_16x16x32_bf16 v[116:119], v[166:169], v[196:199], v[116:119]
	v_mfma_f32_16x16x32_bf16 v[112:115], v[174:177], v[196:199], v[112:115]
	v_mfma_f32_16x16x32_bf16 v[108:111], v[166:169], v[204:207], v[108:111]
	v_mfma_f32_16x16x32_bf16 v[104:107], v[174:177], v[204:207], v[104:107]
	v_mfma_f32_16x16x32_bf16 v[100:103], v[166:169], v[212:215], v[100:103]
	v_mfma_f32_16x16x32_bf16 v[96:99], v[174:177], v[212:215], v[96:99]
	v_mfma_f32_16x16x32_bf16 v[124:127], v[170:173], v[192:195], v[124:127]
	v_mfma_f32_16x16x32_bf16 v[120:123], v[184:187], v[192:195], v[120:123]
	v_mfma_f32_16x16x32_bf16 v[116:119], v[170:173], v[200:203], v[116:119]
	v_mfma_f32_16x16x32_bf16 v[112:115], v[184:187], v[200:203], v[112:115]
	v_mfma_f32_16x16x32_bf16 v[108:111], v[170:173], v[208:211], v[108:111]
	v_mfma_f32_16x16x32_bf16 v[104:107], v[184:187], v[208:211], v[104:107]
	v_mfma_f32_16x16x32_bf16 v[100:103], v[170:173], v[216:219], v[100:103]
	v_mfma_f32_16x16x32_bf16 v[96:99], v[184:187], v[216:219], v[96:99]
	s_barrier
; #define PG8_STAGE(bufoff, gbase, voff) do { _Pragma("unroll") for (int _i = 0; _i < 2; ++_i) \
;         __builtin_amdgcn_global_load_lds((const unsigned*)((const char*)(gbase) + (voff)[_i]), (PG8_LAS unsigned*)(lds + (bufoff) + ldsw + _i * 8192), 16, 0, 0); } while (0)
; #define PG8_LDA(dst, b, h) do { _Pragma("unroll") for (int m = 0; m < 4; ++m) _Pragma("unroll") for (int k = 0; k < 2; ++k) dst[m][k] = *(const PG8_LAS bf16x8*)(lds + PG8_SA(b, h) + aoff + m * 2048 + k * 1024); } while (0)
; #define PG8_MMA(ai, bj, At, Bt) do { __builtin_amdgcn_s_setprio(1); _Pragma("unroll") for (int m = 0; m < 4; ++m) _Pragma("unroll") for (int n = 0; n < 2; ++n) _Pragma("unroll") for (int k = 0; k < 2; ++k) \
;         acc[ai][bj][m][n] = __builtin_amdgcn_mfma_f32_16x16x32_bf16(Bt[n][k], At[m][k], acc[ai][bj][m][n], 0, 0, 0); __builtin_amdgcn_s_setprio(0); } while (0)
; #define PG8_WAIT_V(n) asm volatile("s_waitcnt vmcnt(" #n ")" ::: "memory")
; #define PG8_WAIT_L(n) asm volatile("s_waitcnt lgkmcnt(" #n ")" ::: "memory")
; #define PG8_BAR __builtin_amdgcn_s_barrier()
; #define PG8_SCHED __builtin_amdgcn_sched_barrier(0)
; template <class Epi, class Sched, bool ALIGN_EPI = false, bool SP2 = false>
; __device__ __forceinline__ void gemm_phase(PG8_LAS unsigned char* lds, const Gemm g, const Sched& S, const Epi& E, int tid_in) {
;     ...
;             PG8_LDA(At, 1, 1); PG8_STAGE(PG8_SB(1, 0), b3, voffB); PG8_STAGE(PG8_SB(1, 1), b3 + hstep, voffB); PG8_STAGE(PG8_SA(1, 0), a3, voffA);
;             PG8_WAIT_V(8); PG8_WAIT_L(0); PG8_BAR; PG8_MMA(1, 0, At, B0); PG8_MMA(1, 1, At, B1); PG8_BAR; PG8_SCHED;
	s_add_i32 s50, s53, s29
	s_mov_b32 m0, s50
	ds_read_b128 v[188:191], v182 offset:49152
	global_load_lds_dwordx4 v146, s[98:99]
	s_add_i32 m0, s50, 0x2000
	s_add_u32 s48, s48, 0x40080
	s_addc_u32 s49, s49, 0
	s_add_i32 s50, s88, s29
	global_load_lds_dwordx4 v150, s[98:99]
	s_mov_b32 m0, s50
	ds_read_b128 v[192:195], v182 offset:50176
	global_load_lds_dwordx4 v146, s[48:49]
	s_add_i32 m0, s50, 0x2000
	ds_read_b128 v[196:199], v182 offset:51200
	global_load_lds_dwordx4 v150, s[48:49]
	s_mov_b32 m0, s63
	ds_read_b128 v[200:203], v182 offset:52224
	global_load_lds_dwordx4 v144, s[100:101]
	s_mov_b32 m0, s64
	ds_read_b128 v[204:207], v182 offset:53248
	global_load_lds_dwordx4 v148, s[100:101]
	ds_read_b128 v[208:211], v182 offset:54272
	ds_read_b128 v[212:215], v182 offset:55296
	ds_read_b128 v[216:219], v182 offset:56320
	s_waitcnt vmcnt(8)
	s_waitcnt lgkmcnt(0)
	s_barrier
	v_mfma_f32_16x16x32_bf16 v[28:31], v[128:131], v[188:191], v[28:31]
	v_mfma_f32_16x16x32_bf16 v[24:27], v[136:139], v[188:191], v[24:27]
	v_mfma_f32_16x16x32_bf16 v[20:23], v[128:131], v[196:199], v[20:23]
	v_mfma_f32_16x16x32_bf16 v[16:19], v[136:139], v[196:199], v[16:19]
	v_mfma_f32_16x16x32_bf16 v[12:15], v[128:131], v[204:207], v[12:15]
	v_mfma_f32_16x16x32_bf16 v[8:11], v[136:139], v[204:207], v[8:11]
	v_mfma_f32_16x16x32_bf16 v[4:7], v[128:131], v[212:215], v[4:7]
	v_mfma_f32_16x16x32_bf16 v[0:3], v[136:139], v[212:215], v[0:3]
	v_mfma_f32_16x16x32_bf16 v[28:31], v[132:135], v[192:195], v[28:31]
	v_mfma_f32_16x16x32_bf16 v[24:27], v[140:143], v[192:195], v[24:27]
	v_mfma_f32_16x16x32_bf16 v[20:23], v[132:135], v[200:203], v[20:23]
	v_mfma_f32_16x16x32_bf16 v[16:19], v[140:143], v[200:203], v[16:19]
	v_mfma_f32_16x16x32_bf16 v[12:15], v[132:135], v[208:211], v[12:15]
	v_mfma_f32_16x16x32_bf16 v[8:11], v[140:143], v[208:211], v[8:11]
	v_mfma_f32_16x16x32_bf16 v[4:7], v[132:135], v[216:219], v[4:7]
	v_mfma_f32_16x16x32_bf16 v[0:3], v[140:143], v[216:219], v[0:3]
	v_mfma_f32_16x16x32_bf16 v[92:95], v[166:169], v[188:191], v[92:95]
	v_mfma_f32_16x16x32_bf16 v[88:91], v[174:177], v[188:191], v[88:91]
	v_mfma_f32_16x16x32_bf16 v[84:87], v[166:169], v[196:199], v[84:87]
	v_mfma_f32_16x16x32_bf16 v[80:83], v[174:177], v[196:199], v[80:83]
	v_mfma_f32_16x16x32_bf16 v[76:79], v[166:169], v[204:207], v[76:79]
	v_mfma_f32_16x16x32_bf16 v[72:75], v[174:177], v[204:207], v[72:75]
	v_mfma_f32_16x16x32_bf16 v[64:67], v[166:169], v[212:215], v[64:67]
	v_mfma_f32_16x16x32_bf16 v[60:63], v[174:177], v[212:215], v[60:63]
	v_mfma_f32_16x16x32_bf16 v[92:95], v[170:173], v[192:195], v[92:95]
	v_mfma_f32_16x16x32_bf16 v[88:91], v[184:187], v[192:195], v[88:91]
	v_mfma_f32_16x16x32_bf16 v[84:87], v[170:173], v[200:203], v[84:87]
	v_mfma_f32_16x16x32_bf16 v[80:83], v[184:187], v[200:203], v[80:83]
	v_mfma_f32_16x16x32_bf16 v[76:79], v[170:173], v[208:211], v[76:79]
	v_mfma_f32_16x16x32_bf16 v[72:75], v[184:187], v[208:211], v[72:75]
	v_mfma_f32_16x16x32_bf16 v[64:67], v[170:173], v[216:219], v[64:67]
	v_mfma_f32_16x16x32_bf16 v[60:63], v[184:187], v[216:219], v[60:63]
	s_barrier
	s_add_i32 s52, s52, 2
	s_add_u32 s46, s46, 0x100
	s_addc_u32 s47, s47, 0
	s_add_u32 s35, s35, 0x100
	s_addc_u32 s45, s45, 0

; #define PG8_STAGE(bufoff, gbase, voff) do { _Pragma("unroll") for (int _i = 0; _i < 2; ++_i) \
;         __builtin_amdgcn_global_load_lds((const unsigned*)((const char*)(gbase) + (voff)[_i]), (PG8_LAS unsigned*)(lds + (bufoff) + ldsw + _i * 8192), 16, 0, 0); } while (0)
; #define PG8_LDA(dst, b, h) do { _Pragma("unroll") for (int m = 0; m < 4; ++m) _Pragma("unroll") for (int k = 0; k < 2; ++k) dst[m][k] = *(const PG8_LAS bf16x8*)(lds + PG8_SA(b, h) + aoff + m * 2048 + k * 1024); } while (0)
; #define PG8_WAIT_V(n) asm volatile("s_waitcnt vmcnt(" #n ")" ::: "memory")
; template <class Epi, class Sched, bool ALIGN_EPI = false, bool SP2 = false>
; __device__ __forceinline__ void gemm_phase(PG8_LAS unsigned char* lds, const Gemm g, const Sched& S, const Epi& E, int tid_in) {
;     ...
;         const bool has_next = S.next(ui + 1, nxt);
;         const char* nA = has_next ? (const char*)g.A + (size_t)nxt.pm * tstep : cA; const char* nB = has_next ? (const char*)g.Bt + (size_t)nxt.pn * tstep : cB;
;         for (int t = 0; t < nt; t += 2) {
;             if constexpr (Epi::MIDK) { if (t == Epi::MIDK_T) { if (wr == 0) PG8_BAR; E.mid(acc, cur, wr, wc, fr, fq); if (wr == 1) PG8_BAR; } }
;             const bool last = (t == nt - 2);
;             const char* a1 = cA + (size_t)(t + 1) * kstep;
;             const char* a2 = last ? nA : cA + (size_t)(t + 2) * kstep; const char* b2 = last ? nB : cB + (size_t)(t + 2) * kstep;
;             const char* a3 = a2 + kstep; const char* b3 = b2 + kstep;
;             if (last && has_next) S.a_ready(nxt);
;             if constexpr (SP2) {
;             PG8_LDB(B0, 0, 0); PG8_LDB(B1, 0, 1); PG8_SCHED; PG8_LDA(At, 0, 0); PG8_STAGE(PG8_SA(1, 1), a1 + hstep, voffA);
;             PG8_WAIT_V(8); PG8_WAIT_L(0); PG8_BAR; PG8_MMA(0, 0, At, B0); PG8_MMA(0, 1, At, B1); PG8_BAR; PG8_SCHED;
;             PG8_LDA(At, 0, 1); PG8_STAGE(PG8_SB(0, 0), b2, voffB); PG8_STAGE(PG8_SB(0, 1), b2 + hstep, voffB); PG8_STAGE(PG8_SA(0, 0), a2, voffA);
;             PG8_WAIT_V(8); PG8_WAIT_L(0); PG8_BAR; PG8_MMA(1, 0, At, B0); PG8_MMA(1, 1, At, B1); PG8_BAR; PG8_SCHED;
;     ...
; #pragma unroll
;         for (int a = 0; a < 2; ++a)
; #pragma unroll
;             for (int b = 0; b < 2; ++b)
; #pragma unroll
;                 for (int m = 0; m < 4; ++m)
; #pragma unroll
;                     for (int n = 0; n < 2; ++n) acc[a][b][m][n] = (f32x4){0.f, 0.f, 0.f, 0.f};
.LBB0_1147:
	s_ashr_i32 s23, s22, 31
	s_lshl_b64 s[24:25], s[22:23], 19
	s_add_u32 s24, s38, s24
	s_addc_u32 s25, s39, s25
	s_and_b64 s[26:27], s[4:5], exec
	s_cselect_b32 s23, s25, s31
	s_cselect_b32 s29, s24, s30
	s_ashr_i32 s21, s20, 31
	s_lshl_b64 s[26:27], s[20:21], 19
	s_add_u32 s26, s44, s26
	s_addc_u32 s27, s45, s27
	s_and_b64 s[36:37], s[4:5], exec
	s_cselect_b32 s21, s27, s35
	s_cselect_b32 s57, s26, s34
	s_add_u32 s30, s30, 0x40080
	s_addc_u32 s31, s31, 0
	s_add_u32 s58, s34, 0x100
	s_addc_u32 s59, s35, 0
	s_mov_b32 s60, -2
	s_waitcnt lgkmcnt(0)
	s_add_u32 s34, s30, 0xfffc0080
	s_addc_u32 s35, s31, -1
	s_cmp_eq_u32 s60, 12
	s_cselect_b32 s37, s23, s35
	s_cselect_b32 s36, s29, s34
	s_cselect_b32 s35, s21, s59
	s_cselect_b32 s34, s57, s58
	s_add_i32 m0, s1, 0xc000
	ds_read_b128 v[128:131], v191
	global_load_lds_dwordx4 v160, s[30:31]
	s_add_i32 m0, s1, 0xe000
	ds_read_b128 v[132:135], v191 offset:1024
	global_load_lds_dwordx4 v162, s[30:31]
	ds_read_b128 v[136:139], v191 offset:2048
	ds_read_b128 v[140:143], v191 offset:3072
	ds_read_b128 v[144:147], v192
	ds_read_b128 v[148:151], v192 offset:1024
	ds_read_b128 v[168:171], v192 offset:2048
	ds_read_b128 v[172:175], v192 offset:3072
	ds_read_b128 v[176:179], v193
	ds_read_b128 v[180:183], v193 offset:1024
	ds_read_b128 v[194:197], v193 offset:2048
	ds_read_b128 v[198:201], v193 offset:3072
	ds_read_b128 v[202:205], v193 offset:4096
	ds_read_b128 v[206:209], v193 offset:5120
	ds_read_b128 v[210:213], v193 offset:6144
	ds_read_b128 v[214:217], v193 offset:7168
	s_waitcnt vmcnt(8)
	s_waitcnt lgkmcnt(0)
	s_barrier
	v_mfma_f32_16x16x32_bf16 v[124:127], v[128:131], v[176:179], 0
	v_mfma_f32_16x16x32_bf16 v[120:123], v[136:139], v[176:179], 0
	v_mfma_f32_16x16x32_bf16 v[108:111], v[128:131], v[194:197], 0
	v_mfma_f32_16x16x32_bf16 v[104:107], v[136:139], v[194:197], 0
	v_mfma_f32_16x16x32_bf16 v[92:95], v[128:131], v[202:205], 0
	v_mfma_f32_16x16x32_bf16 v[88:91], v[136:139], v[202:205], 0
	v_mfma_f32_16x16x32_bf16 v[76:79], v[128:131], v[210:213], 0
	v_mfma_f32_16x16x32_bf16 v[72:75], v[136:139], v[210:213], 0
	v_mfma_f32_16x16x32_bf16 v[124:127], v[132:135], v[180:183], v[124:127]
	v_mfma_f32_16x16x32_bf16 v[120:123], v[140:143], v[180:183], v[120:123]
	v_mfma_f32_16x16x32_bf16 v[108:111], v[132:135], v[198:201], v[108:111]
	v_mfma_f32_16x16x32_bf16 v[104:107], v[140:143], v[198:201], v[104:107]
	v_mfma_f32_16x16x32_bf16 v[92:95], v[132:135], v[206:209], v[92:95]
	v_mfma_f32_16x16x32_bf16 v[88:91], v[140:143], v[206:209], v[88:91]
	v_mfma_f32_16x16x32_bf16 v[76:79], v[132:135], v[214:217], v[76:79]
	v_mfma_f32_16x16x32_bf16 v[72:75], v[140:143], v[214:217], v[72:75]
	v_mfma_f32_16x16x32_bf16 v[116:119], v[144:147], v[176:179], 0
	v_mfma_f32_16x16x32_bf16 v[112:115], v[168:171], v[176:179], 0
	v_mfma_f32_16x16x32_bf16 v[100:103], v[144:147], v[194:197], 0
	v_mfma_f32_16x16x32_bf16 v[96:99], v[168:171], v[194:197], 0
	v_mfma_f32_16x16x32_bf16 v[84:87], v[144:147], v[202:205], 0
	v_mfma_f32_16x16x32_bf16 v[80:83], v[168:171], v[202:205], 0
	v_mfma_f32_16x16x32_bf16 v[68:71], v[144:147], v[210:213], 0
	v_mfma_f32_16x16x32_bf16 v[64:67], v[168:171], v[210:213], 0
	v_mfma_f32_16x16x32_bf16 v[116:119], v[148:151], v[180:183], v[116:119]
	v_mfma_f32_16x16x32_bf16 v[112:115], v[172:175], v[180:183], v[112:115]
	v_mfma_f32_16x16x32_bf16 v[100:103], v[148:151], v[198:201], v[100:103]
	v_mfma_f32_16x16x32_bf16 v[96:99], v[172:175], v[198:201], v[96:99]
	v_mfma_f32_16x16x32_bf16 v[84:87], v[148:151], v[206:209], v[84:87]
	v_mfma_f32_16x16x32_bf16 v[80:83], v[172:175], v[206:209], v[80:83]
	v_mfma_f32_16x16x32_bf16 v[68:71], v[148:151], v[214:217], v[68:71]
	v_mfma_f32_16x16x32_bf16 v[64:67], v[172:175], v[214:217], v[64:67]
	s_barrier
	s_add_u32 s98, s34, s16
	s_addc_u32 s99, s35, s17
	s_add_u32 s100, s36, s16
	s_addc_u32 s101, s37, s17
	s_add_i32 s61, s54, s0
	s_mov_b32 m0, s61
	ds_read_b128 v[176:179], v193 offset:16384
	global_load_lds_dwordx4 v154, s[34:35]
	s_add_i32 m0, s61, 0x2000
	s_add_u32 s62, s34, 0x40000
	s_addc_u32 s63, s35, 0
	s_add_i32 s61, s55, s0
	global_load_lds_dwordx4 v158, s[34:35]
	s_mov_b32 m0, s61
	ds_read_b128 v[180:183], v193 offset:17408
	global_load_lds_dwordx4 v154, s[62:63]
	s_add_i32 m0, s61, 0x2000
	ds_read_b128 v[194:197], v193 offset:18432
	global_load_lds_dwordx4 v158, s[62:63]
	s_mov_b32 m0, s1
	ds_read_b128 v[198:201], v193 offset:19456
	global_load_lds_dwordx4 v152, s[36:37]
	s_mov_b32 m0, s46
	ds_read_b128 v[202:205], v193 offset:20480
	global_load_lds_dwordx4 v156, s[36:37]
	ds_read_b128 v[206:209], v193 offset:21504
	ds_read_b128 v[210:213], v193 offset:22528
	ds_read_b128 v[214:217], v193 offset:23552
	s_waitcnt vmcnt(8)
	s_waitcnt lgkmcnt(0)
	s_barrier
; #define PG8_STAGE(bufoff, gbase, voff) do { _Pragma("unroll") for (int _i = 0; _i < 2; ++_i) \
;         __builtin_amdgcn_global_load_lds((const unsigned*)((const char*)(gbase) + (voff)[_i]), (PG8_LAS unsigned*)(lds + (bufoff) + ldsw + _i * 8192), 16, 0, 0); } while (0)
; #define PG8_LDA(dst, b, h) do { _Pragma("unroll") for (int m = 0; m < 4; ++m) _Pragma("unroll") for (int k = 0; k < 2; ++k) dst[m][k] = *(const PG8_LAS bf16x8*)(lds + PG8_SA(b, h) + aoff + m * 2048 + k * 1024); } while (0)
; #define PG8_LDB(dst, b, h) do { _Pragma("unroll") for (int n = 0; n < 2; ++n) _Pragma("unroll") for (int k = 0; k < 2; ++k) dst[n][k] = *(const PG8_LAS bf16x8*)(lds + PG8_SB(b, h) + boff + n * 2048 + k * 1024); } while (0)
; #define PG8_MMA(ai, bj, At, Bt) do { __builtin_amdgcn_s_setprio(1); _Pragma("unroll") for (int m = 0; m < 4; ++m) _Pragma("unroll") for (int n = 0; n < 2; ++n) _Pragma("unroll") for (int k = 0; k < 2; ++k) \
;         acc[ai][bj][m][n] = __builtin_amdgcn_mfma_f32_16x16x32_bf16(Bt[n][k], At[m][k], acc[ai][bj][m][n], 0, 0, 0); __builtin_amdgcn_s_setprio(0); } while (0)
; #define PG8_WAIT_V(n) asm volatile("s_waitcnt vmcnt(" #n ")" ::: "memory")
; #define PG8_WAIT_L(n) asm volatile("s_waitcnt lgkmcnt(" #n ")" ::: "memory")
; template <class Epi, class Sched, bool ALIGN_EPI = false, bool SP2 = false>
; __device__ __forceinline__ void gemm_phase(PG8_LAS unsigned char* lds, const Gemm g, const Sched& S, const Epi& E, int tid_in) {
;     ...
;             PG8_WAIT_V(8); PG8_WAIT_L(0); PG8_BAR; PG8_MMA(0, 0, At, B0); PG8_MMA(0, 1, At, B1); PG8_BAR; PG8_SCHED;
;             PG8_LDA(At, 0, 1); PG8_STAGE(PG8_SB(0, 0), b2, voffB); PG8_STAGE(PG8_SB(0, 1), b2 + hstep, voffB); PG8_STAGE(PG8_SA(0, 0), a2, voffA);
;             PG8_WAIT_V(8); PG8_WAIT_L(0); PG8_BAR; PG8_MMA(1, 0, At, B0); PG8_MMA(1, 1, At, B1); PG8_BAR; PG8_SCHED;
;             PG8_LDB(B0, 1, 0); PG8_LDB(B1, 1, 1); PG8_SCHED; PG8_LDA(At, 1, 0); PG8_STAGE(PG8_SA(0, 1), a2 + hstep, voffA);
;             PG8_WAIT_V(8); PG8_WAIT_L(0); PG8_BAR; PG8_MMA(0, 0, At, B0); PG8_MMA(0, 1, At, B1); PG8_BAR; PG8_SCHED;
;             PG8_LDA(At, 1, 1); PG8_STAGE(PG8_SB(1, 0), b3, voffB); PG8_STAGE(PG8_SB(1, 1), b3 + hstep, voffB); PG8_STAGE(PG8_SA(1, 0), a3, voffA);
;             PG8_WAIT_V(8); PG8_WAIT_L(0); PG8_BAR; PG8_MMA(1, 0, At, B0); PG8_MMA(1, 1, At, B1); PG8_BAR; PG8_SCHED;
	v_mfma_f32_16x16x32_bf16 v[60:63], v[128:131], v[176:179], 0
	v_mfma_f32_16x16x32_bf16 v[56:59], v[136:139], v[176:179], 0
	v_mfma_f32_16x16x32_bf16 v[44:47], v[128:131], v[194:197], 0
	v_mfma_f32_16x16x32_bf16 v[40:43], v[136:139], v[194:197], 0
	v_mfma_f32_16x16x32_bf16 v[28:31], v[128:131], v[202:205], 0
	v_mfma_f32_16x16x32_bf16 v[24:27], v[136:139], v[202:205], 0
	v_mfma_f32_16x16x32_bf16 v[12:15], v[128:131], v[210:213], 0
	v_mfma_f32_16x16x32_bf16 v[8:11], v[136:139], v[210:213], 0
	v_mfma_f32_16x16x32_bf16 v[60:63], v[132:135], v[180:183], v[60:63]
	v_mfma_f32_16x16x32_bf16 v[56:59], v[140:143], v[180:183], v[56:59]
	v_mfma_f32_16x16x32_bf16 v[44:47], v[132:135], v[198:201], v[44:47]
	v_mfma_f32_16x16x32_bf16 v[40:43], v[140:143], v[198:201], v[40:43]
	v_mfma_f32_16x16x32_bf16 v[28:31], v[132:135], v[206:209], v[28:31]
	v_mfma_f32_16x16x32_bf16 v[24:27], v[140:143], v[206:209], v[24:27]
	v_mfma_f32_16x16x32_bf16 v[12:15], v[132:135], v[214:217], v[12:15]
	v_mfma_f32_16x16x32_bf16 v[8:11], v[140:143], v[214:217], v[8:11]
	v_mfma_f32_16x16x32_bf16 v[52:55], v[144:147], v[176:179], 0
	v_mfma_f32_16x16x32_bf16 v[48:51], v[168:171], v[176:179], 0
	v_mfma_f32_16x16x32_bf16 v[36:39], v[144:147], v[194:197], 0
	v_mfma_f32_16x16x32_bf16 v[32:35], v[168:171], v[194:197], 0
	v_mfma_f32_16x16x32_bf16 v[20:23], v[144:147], v[202:205], 0
	v_mfma_f32_16x16x32_bf16 v[16:19], v[168:171], v[202:205], 0
	v_mfma_f32_16x16x32_bf16 v[4:7], v[144:147], v[210:213], 0
	v_mfma_f32_16x16x32_bf16 v[0:3], v[168:171], v[210:213], 0
	v_mfma_f32_16x16x32_bf16 v[52:55], v[148:151], v[180:183], v[52:55]
	v_mfma_f32_16x16x32_bf16 v[48:51], v[172:175], v[180:183], v[48:51]
	v_mfma_f32_16x16x32_bf16 v[36:39], v[148:151], v[198:201], v[36:39]
	v_mfma_f32_16x16x32_bf16 v[32:35], v[172:175], v[198:201], v[32:35]
	v_mfma_f32_16x16x32_bf16 v[20:23], v[148:151], v[206:209], v[20:23]
	v_mfma_f32_16x16x32_bf16 v[16:19], v[172:175], v[206:209], v[16:19]
	v_mfma_f32_16x16x32_bf16 v[4:7], v[148:151], v[214:217], v[4:7]
	v_mfma_f32_16x16x32_bf16 v[0:3], v[172:175], v[214:217], v[0:3]
	s_barrier
	s_add_i32 s61, 0, 0x18000
	s_add_i32 s62, 0, 0x1c000
	s_add_u32 s36, s36, 0x40000
	s_addc_u32 s37, s37, 0
	s_mov_b32 m0, s47
	s_nop 0
	global_load_lds_dwordx4 v152, s[36:37]
	s_mov_b32 m0, s48
	s_nop 0
	global_load_lds_dwordx4 v156, s[36:37]
	v_add_u32_e32 v140, s61, v187
	v_add_u32_e32 v172, s62, v187
	ds_read_b128 v[128:131], v140
	ds_read_b128 v[132:135], v140 offset:1024
	ds_read_b128 v[136:139], v140 offset:2048
	ds_read_b128 v[140:143], v140 offset:3072
	ds_read_b128 v[144:147], v172
	ds_read_b128 v[148:151], v172 offset:1024
	ds_read_b128 v[168:171], v172 offset:2048
	ds_read_b128 v[172:175], v172 offset:3072
	ds_read_b128 v[176:179], v193 offset:32768
	ds_read_b128 v[180:183], v193 offset:33792
	ds_read_b128 v[194:197], v193 offset:34816
	ds_read_b128 v[198:201], v193 offset:35840
	ds_read_b128 v[202:205], v193 offset:36864
	ds_read_b128 v[206:209], v193 offset:37888
	ds_read_b128 v[210:213], v193 offset:38912
	ds_read_b128 v[214:217], v193 offset:39936
	s_waitcnt vmcnt(8)
	s_waitcnt lgkmcnt(0)
	s_barrier
	v_mfma_f32_16x16x32_bf16 v[124:127], v[128:131], v[176:179], v[124:127]
	v_mfma_f32_16x16x32_bf16 v[120:123], v[136:139], v[176:179], v[120:123]
	v_mfma_f32_16x16x32_bf16 v[108:111], v[128:131], v[194:197], v[108:111]
	v_mfma_f32_16x16x32_bf16 v[104:107], v[136:139], v[194:197], v[104:107]
	v_mfma_f32_16x16x32_bf16 v[92:95], v[128:131], v[202:205], v[92:95]
	v_mfma_f32_16x16x32_bf16 v[88:91], v[136:139], v[202:205], v[88:91]
	v_mfma_f32_16x16x32_bf16 v[76:79], v[128:131], v[210:213], v[76:79]
	v_mfma_f32_16x16x32_bf16 v[72:75], v[136:139], v[210:213], v[72:75]
	v_mfma_f32_16x16x32_bf16 v[124:127], v[132:135], v[180:183], v[124:127]
	v_mfma_f32_16x16x32_bf16 v[120:123], v[140:143], v[180:183], v[120:123]
	v_mfma_f32_16x16x32_bf16 v[108:111], v[132:135], v[198:201], v[108:111]
	v_mfma_f32_16x16x32_bf16 v[104:107], v[140:143], v[198:201], v[104:107]
	v_mfma_f32_16x16x32_bf16 v[92:95], v[132:135], v[206:209], v[92:95]
	v_mfma_f32_16x16x32_bf16 v[88:91], v[140:143], v[206:209], v[88:91]
	v_mfma_f32_16x16x32_bf16 v[76:79], v[132:135], v[214:217], v[76:79]
	v_mfma_f32_16x16x32_bf16 v[72:75], v[140:143], v[214:217], v[72:75]
	v_mfma_f32_16x16x32_bf16 v[116:119], v[144:147], v[176:179], v[116:119]
	v_mfma_f32_16x16x32_bf16 v[112:115], v[168:171], v[176:179], v[112:115]
	v_mfma_f32_16x16x32_bf16 v[100:103], v[144:147], v[194:197], v[100:103]
	v_mfma_f32_16x16x32_bf16 v[96:99], v[168:171], v[194:197], v[96:99]
	v_mfma_f32_16x16x32_bf16 v[84:87], v[144:147], v[202:205], v[84:87]
	v_mfma_f32_16x16x32_bf16 v[80:83], v[168:171], v[202:205], v[80:83]
	v_mfma_f32_16x16x32_bf16 v[68:71], v[144:147], v[210:213], v[68:71]
	v_mfma_f32_16x16x32_bf16 v[64:67], v[168:171], v[210:213], v[64:67]
	v_mfma_f32_16x16x32_bf16 v[116:119], v[148:151], v[180:183], v[116:119]
	v_mfma_f32_16x16x32_bf16 v[112:115], v[172:175], v[180:183], v[112:115]
	v_mfma_f32_16x16x32_bf16 v[100:103], v[148:151], v[198:201], v[100:103]
	v_mfma_f32_16x16x32_bf16 v[96:99], v[172:175], v[198:201], v[96:99]
	v_mfma_f32_16x16x32_bf16 v[84:87], v[148:151], v[206:209], v[84:87]
	v_mfma_f32_16x16x32_bf16 v[80:83], v[172:175], v[206:209], v[80:83]
	v_mfma_f32_16x16x32_bf16 v[68:71], v[148:151], v[214:217], v[68:71]
	v_mfma_f32_16x16x32_bf16 v[64:67], v[172:175], v[214:217], v[64:67]
	s_barrier
; #define PG8_STAGE(bufoff, gbase, voff) do { _Pragma("unroll") for (int _i = 0; _i < 2; ++_i) \
;         __builtin_amdgcn_global_load_lds((const unsigned*)((const char*)(gbase) + (voff)[_i]), (PG8_LAS unsigned*)(lds + (bufoff) + ldsw + _i * 8192), 16, 0, 0); } while (0)
; #define PG8_LDA(dst, b, h) do { _Pragma("unroll") for (int m = 0; m < 4; ++m) _Pragma("unroll") for (int k = 0; k < 2; ++k) dst[m][k] = *(const PG8_LAS bf16x8*)(lds + PG8_SA(b, h) + aoff + m * 2048 + k * 1024); } while (0)
; #define PG8_MMA(ai, bj, At, Bt) do { __builtin_amdgcn_s_setprio(1); _Pragma("unroll") for (int m = 0; m < 4; ++m) _Pragma("unroll") for (int n = 0; n < 2; ++n) _Pragma("unroll") for (int k = 0; k < 2; ++k) \
;         acc[ai][bj][m][n] = __builtin_amdgcn_mfma_f32_16x16x32_bf16(Bt[n][k], At[m][k], acc[ai][bj][m][n], 0, 0, 0); __builtin_amdgcn_s_setprio(0); } while (0)
; #define PG8_WAIT_V(n) asm volatile("s_waitcnt vmcnt(" #n ")" ::: "memory")
; #define PG8_WAIT_L(n) asm volatile("s_waitcnt lgkmcnt(" #n ")" ::: "memory")
; #define PG8_BAR __builtin_amdgcn_s_barrier()
; #define PG8_SCHED __builtin_amdgcn_sched_barrier(0)
; template <class Epi, class Sched, bool ALIGN_EPI = false, bool SP2 = false>
; __device__ __forceinline__ void gemm_phase(PG8_LAS unsigned char* lds, const Gemm g, const Sched& S, const Epi& E, int tid_in) {
;     ...
;             PG8_LDA(At, 1, 1); PG8_STAGE(PG8_SB(1, 0), b3, voffB); PG8_STAGE(PG8_SB(1, 1), b3 + hstep, voffB); PG8_STAGE(PG8_SA(1, 0), a3, voffA);
;             PG8_WAIT_V(8); PG8_WAIT_L(0); PG8_BAR; PG8_MMA(1, 0, At, B0); PG8_MMA(1, 1, At, B1); PG8_BAR; PG8_SCHED;
	s_add_i32 s36, s61, s0
	s_mov_b32 m0, s36
	ds_read_b128 v[176:179], v193 offset:49152
	global_load_lds_dwordx4 v154, s[98:99]
	s_add_i32 m0, s36, 0x2000
	s_add_u32 s34, s34, 0x40080
	s_addc_u32 s35, s35, 0
	s_add_i32 s36, s62, s0
	global_load_lds_dwordx4 v158, s[98:99]
	s_mov_b32 m0, s36
	ds_read_b128 v[180:183], v193 offset:50176
	global_load_lds_dwordx4 v154, s[34:35]
	s_add_i32 m0, s36, 0x2000
	ds_read_b128 v[194:197], v193 offset:51200
	global_load_lds_dwordx4 v158, s[34:35]
	s_mov_b32 m0, s50
	ds_read_b128 v[198:201], v193 offset:52224
	global_load_lds_dwordx4 v152, s[100:101]
	s_mov_b32 m0, s51
	ds_read_b128 v[202:205], v193 offset:53248
	global_load_lds_dwordx4 v156, s[100:101]
	ds_read_b128 v[206:209], v193 offset:54272
	ds_read_b128 v[210:213], v193 offset:55296
	ds_read_b128 v[214:217], v193 offset:56320
	s_waitcnt vmcnt(8)
	s_waitcnt lgkmcnt(0)
	s_barrier
	v_mfma_f32_16x16x32_bf16 v[60:63], v[128:131], v[176:179], v[60:63]
	v_mfma_f32_16x16x32_bf16 v[56:59], v[136:139], v[176:179], v[56:59]
	v_mfma_f32_16x16x32_bf16 v[44:47], v[128:131], v[194:197], v[44:47]
	v_mfma_f32_16x16x32_bf16 v[40:43], v[136:139], v[194:197], v[40:43]
	v_mfma_f32_16x16x32_bf16 v[28:31], v[128:131], v[202:205], v[28:31]
	v_mfma_f32_16x16x32_bf16 v[24:27], v[136:139], v[202:205], v[24:27]
	v_mfma_f32_16x16x32_bf16 v[12:15], v[128:131], v[210:213], v[12:15]
	v_mfma_f32_16x16x32_bf16 v[8:11], v[136:139], v[210:213], v[8:11]
	v_mfma_f32_16x16x32_bf16 v[60:63], v[132:135], v[180:183], v[60:63]
	v_mfma_f32_16x16x32_bf16 v[56:59], v[140:143], v[180:183], v[56:59]
	v_mfma_f32_16x16x32_bf16 v[44:47], v[132:135], v[198:201], v[44:47]
	v_mfma_f32_16x16x32_bf16 v[40:43], v[140:143], v[198:201], v[40:43]
	v_mfma_f32_16x16x32_bf16 v[28:31], v[132:135], v[206:209], v[28:31]
	v_mfma_f32_16x16x32_bf16 v[24:27], v[140:143], v[206:209], v[24:27]
	v_mfma_f32_16x16x32_bf16 v[12:15], v[132:135], v[214:217], v[12:15]
	v_mfma_f32_16x16x32_bf16 v[8:11], v[140:143], v[214:217], v[8:11]
	v_mfma_f32_16x16x32_bf16 v[52:55], v[144:147], v[176:179], v[52:55]
	v_mfma_f32_16x16x32_bf16 v[48:51], v[168:171], v[176:179], v[48:51]
	v_mfma_f32_16x16x32_bf16 v[36:39], v[144:147], v[194:197], v[36:39]
	v_mfma_f32_16x16x32_bf16 v[32:35], v[168:171], v[194:197], v[32:35]
	v_mfma_f32_16x16x32_bf16 v[20:23], v[144:147], v[202:205], v[20:23]
	v_mfma_f32_16x16x32_bf16 v[16:19], v[168:171], v[202:205], v[16:19]
	v_mfma_f32_16x16x32_bf16 v[4:7], v[144:147], v[210:213], v[4:7]
	v_mfma_f32_16x16x32_bf16 v[0:3], v[168:171], v[210:213], v[0:3]
	v_mfma_f32_16x16x32_bf16 v[52:55], v[148:151], v[180:183], v[52:55]
	v_mfma_f32_16x16x32_bf16 v[48:51], v[172:175], v[180:183], v[48:51]
	v_mfma_f32_16x16x32_bf16 v[36:39], v[148:151], v[198:201], v[36:39]
	v_mfma_f32_16x16x32_bf16 v[32:35], v[172:175], v[198:201], v[32:35]
	v_mfma_f32_16x16x32_bf16 v[20:23], v[148:151], v[206:209], v[20:23]
	v_mfma_f32_16x16x32_bf16 v[16:19], v[172:175], v[206:209], v[16:19]
	v_mfma_f32_16x16x32_bf16 v[4:7], v[148:151], v[214:217], v[4:7]
	v_mfma_f32_16x16x32_bf16 v[0:3], v[172:175], v[214:217], v[0:3]
	s_barrier
	s_add_i32 s60, s60, 2
	s_add_u32 s30, s30, 0x100
	s_addc_u32 s31, s31, 0
	s_add_u32 s58, s58, 0x100
	s_addc_u32 s59, s59, 0

; #define PG8_STAGE(bufoff, gbase, voff) do { _Pragma("unroll") for (int _i = 0; _i < 2; ++_i) \
;         __builtin_amdgcn_global_load_lds((const unsigned*)((const char*)(gbase) + (voff)[_i]), (PG8_LAS unsigned*)(lds + (bufoff) + ldsw + _i * 8192), 16, 0, 0); } while (0)
; #define PG8_LDA(dst, b, h) do { _Pragma("unroll") for (int m = 0; m < 4; ++m) _Pragma("unroll") for (int k = 0; k < 2; ++k) dst[m][k] = *(const PG8_LAS bf16x8*)(lds + PG8_SA(b, h) + aoff + m * 2048 + k * 1024); } while (0)
; #define PG8_WAIT_V(n) asm volatile("s_waitcnt vmcnt(" #n ")" ::: "memory")
; template <class Epi, class Sched, bool ALIGN_EPI = false, bool SP2 = false>
; __device__ __forceinline__ void gemm_phase(PG8_LAS unsigned char* lds, const Gemm g, const Sched& S, const Epi& E, int tid_in) {
;     ...
;         const bool has_next = S.next(ui + 1, nxt);
;         const char* nA = has_next ? (const char*)g.A + (size_t)nxt.pm * tstep : cA; const char* nB = has_next ? (const char*)g.Bt + (size_t)nxt.pn * tstep : cB;
;         for (int t = 0; t < nt; t += 2) {
;             if constexpr (Epi::MIDK) { if (t == Epi::MIDK_T) { if (wr == 0) PG8_BAR; E.mid(acc, cur, wr, wc, fr, fq); if (wr == 1) PG8_BAR; } }
;             const bool last = (t == nt - 2);
;             const char* a1 = cA + (size_t)(t + 1) * kstep;
;             const char* a2 = last ? nA : cA + (size_t)(t + 2) * kstep; const char* b2 = last ? nB : cB + (size_t)(t + 2) * kstep;
;             const char* a3 = a2 + kstep; const char* b3 = b2 + kstep;
;             if (last && has_next) S.a_ready(nxt);
;             if constexpr (SP2) {
;             PG8_LDB(B0, 0, 0); PG8_LDB(B1, 0, 1); PG8_SCHED; PG8_LDA(At, 0, 0); PG8_STAGE(PG8_SA(1, 1), a1 + hstep, voffA);
;             PG8_WAIT_V(8); PG8_WAIT_L(0); PG8_BAR; PG8_MMA(0, 0, At, B0); PG8_MMA(0, 1, At, B1); PG8_BAR; PG8_SCHED;
;             PG8_LDA(At, 0, 1); PG8_STAGE(PG8_SB(0, 0), b2, voffB); PG8_STAGE(PG8_SB(0, 1), b2 + hstep, voffB); PG8_STAGE(PG8_SA(0, 0), a2, voffA);
;             PG8_WAIT_V(8); PG8_WAIT_L(0); PG8_BAR; PG8_MMA(1, 0, At, B0); PG8_MMA(1, 1, At, B1); PG8_BAR; PG8_SCHED;
;     ...
; #pragma unroll
;         for (int a = 0; a < 2; ++a)
; #pragma unroll
;             for (int b = 0; b < 2; ++b)
; #pragma unroll
;                 for (int m = 0; m < 4; ++m)
; #pragma unroll
;                     for (int n = 0; n < 2; ++n) acc[a][b][m][n] = (f32x4){0.f, 0.f, 0.f, 0.f};
.LBB0_1237:
	s_ashr_i32 s17, s16, 31
	s_lshl_b64 s[18:19], s[16:17], 19
	s_add_u32 s18, s1, s18
	s_addc_u32 s19, s30, s19
	s_and_b64 s[20:21], s[2:3], exec
	s_cselect_b32 s17, s19, s25
	s_cselect_b32 s54, s18, s24
	s_ashr_i32 s15, s14, 31
	s_lshl_b64 s[20:21], s[14:15], 19
	s_add_u32 s20, s31, s20
	s_addc_u32 s21, s34, s21
	s_and_b64 s[28:29], s[2:3], exec
	s_cselect_b32 s15, s21, s27
	s_cselect_b32 s55, s20, s26
	s_add_u32 s24, s24, 0x40080
	s_addc_u32 s25, s25, 0
	s_add_u32 s56, s26, 0x100
	s_addc_u32 s57, s27, 0
	s_mov_b32 s58, -2
	s_add_u32 s26, s24, 0xfffc0080
	s_addc_u32 s27, s25, -1
	s_cmp_eq_u32 s58, 12
	s_cselect_b32 s29, s17, s27
	s_cselect_b32 s28, s54, s26
	s_cselect_b32 s27, s15, s57
	s_cselect_b32 s26, s55, s56
	s_add_i32 m0, s23, 0xc000
	ds_read_b128 v[144:147], v154
	global_load_lds_dwordx4 v136, s[24:25]
	s_add_i32 m0, s23, 0xe000
	ds_read_b128 v[158:161], v154 offset:1024
	global_load_lds_dwordx4 v138, s[24:25]
	ds_read_b128 v[162:165], v154 offset:2048
	ds_read_b128 v[166:169], v154 offset:3072
	ds_read_b128 v[170:173], v155
	ds_read_b128 v[174:177], v155 offset:1024
	ds_read_b128 v[178:181], v155 offset:2048
	ds_read_b128 v[182:185], v155 offset:3072
	ds_read_b128 v[186:189], v156
	ds_read_b128 v[190:193], v156 offset:1024
	ds_read_b128 v[194:197], v156 offset:2048
	ds_read_b128 v[198:201], v156 offset:3072
	ds_read_b128 v[202:205], v156 offset:4096
	ds_read_b128 v[206:209], v156 offset:5120
	ds_read_b128 v[210:213], v156 offset:6144
	ds_read_b128 v[214:217], v156 offset:7168
	s_waitcnt vmcnt(8)
	s_waitcnt lgkmcnt(0)
	s_barrier
	v_mfma_f32_16x16x32_bf16 v[124:127], v[144:147], v[186:189], 0
	v_mfma_f32_16x16x32_bf16 v[120:123], v[162:165], v[186:189], 0
	v_mfma_f32_16x16x32_bf16 v[108:111], v[144:147], v[194:197], 0
	v_mfma_f32_16x16x32_bf16 v[104:107], v[162:165], v[194:197], 0
	v_mfma_f32_16x16x32_bf16 v[92:95], v[144:147], v[202:205], 0
	v_mfma_f32_16x16x32_bf16 v[88:91], v[162:165], v[202:205], 0
	v_mfma_f32_16x16x32_bf16 v[76:79], v[144:147], v[210:213], 0
	v_mfma_f32_16x16x32_bf16 v[72:75], v[162:165], v[210:213], 0
	v_mfma_f32_16x16x32_bf16 v[124:127], v[158:161], v[190:193], v[124:127]
	v_mfma_f32_16x16x32_bf16 v[120:123], v[166:169], v[190:193], v[120:123]
	v_mfma_f32_16x16x32_bf16 v[108:111], v[158:161], v[198:201], v[108:111]
	v_mfma_f32_16x16x32_bf16 v[104:107], v[166:169], v[198:201], v[104:107]
	v_mfma_f32_16x16x32_bf16 v[92:95], v[158:161], v[206:209], v[92:95]
	v_mfma_f32_16x16x32_bf16 v[88:91], v[166:169], v[206:209], v[88:91]
	v_mfma_f32_16x16x32_bf16 v[76:79], v[158:161], v[214:217], v[76:79]
	v_mfma_f32_16x16x32_bf16 v[72:75], v[166:169], v[214:217], v[72:75]
	v_mfma_f32_16x16x32_bf16 v[116:119], v[170:173], v[186:189], 0
	v_mfma_f32_16x16x32_bf16 v[112:115], v[178:181], v[186:189], 0
	v_mfma_f32_16x16x32_bf16 v[100:103], v[170:173], v[194:197], 0
	v_mfma_f32_16x16x32_bf16 v[96:99], v[178:181], v[194:197], 0
	v_mfma_f32_16x16x32_bf16 v[84:87], v[170:173], v[202:205], 0
	v_mfma_f32_16x16x32_bf16 v[80:83], v[178:181], v[202:205], 0
	v_mfma_f32_16x16x32_bf16 v[68:71], v[170:173], v[210:213], 0
	v_mfma_f32_16x16x32_bf16 v[64:67], v[178:181], v[210:213], 0
	v_mfma_f32_16x16x32_bf16 v[116:119], v[174:177], v[190:193], v[116:119]
	v_mfma_f32_16x16x32_bf16 v[112:115], v[182:185], v[190:193], v[112:115]
	v_mfma_f32_16x16x32_bf16 v[100:103], v[174:177], v[198:201], v[100:103]
	v_mfma_f32_16x16x32_bf16 v[96:99], v[182:185], v[198:201], v[96:99]
	v_mfma_f32_16x16x32_bf16 v[84:87], v[174:177], v[206:209], v[84:87]
	v_mfma_f32_16x16x32_bf16 v[80:83], v[182:185], v[206:209], v[80:83]
	v_mfma_f32_16x16x32_bf16 v[68:71], v[174:177], v[214:217], v[68:71]
	v_mfma_f32_16x16x32_bf16 v[64:67], v[182:185], v[214:217], v[64:67]
	s_barrier
	s_add_u32 s98, s26, s10
	s_addc_u32 s99, s27, s11
	s_add_u32 s100, s28, s10
	s_addc_u32 s101, s29, s11
	s_add_i32 s59, s47, s0
	s_mov_b32 m0, s59
	ds_read_b128 v[186:189], v156 offset:16384
	global_load_lds_dwordx4 v132, s[26:27]
	s_add_i32 m0, s59, 0x2000
	s_add_u32 s60, s26, 0x40000
	s_addc_u32 s61, s27, 0
	s_add_i32 s59, s48, s0
	global_load_lds_dwordx4 v128, s[26:27]
	s_mov_b32 m0, s59
	ds_read_b128 v[190:193], v156 offset:17408
	global_load_lds_dwordx4 v132, s[60:61]
	s_add_i32 m0, s59, 0x2000
	ds_read_b128 v[194:197], v156 offset:18432
	global_load_lds_dwordx4 v128, s[60:61]
	s_mov_b32 m0, s23
	ds_read_b128 v[198:201], v156 offset:19456
	global_load_lds_dwordx4 v134, s[28:29]
	s_mov_b32 m0, s37
	ds_read_b128 v[202:205], v156 offset:20480
	global_load_lds_dwordx4 v130, s[28:29]
	ds_read_b128 v[206:209], v156 offset:21504
	ds_read_b128 v[210:213], v156 offset:22528
	ds_read_b128 v[214:217], v156 offset:23552
	s_waitcnt vmcnt(8)
	s_waitcnt lgkmcnt(0)
	s_barrier
; #define PG8_STAGE(bufoff, gbase, voff) do { _Pragma("unroll") for (int _i = 0; _i < 2; ++_i) \
;         __builtin_amdgcn_global_load_lds((const unsigned*)((const char*)(gbase) + (voff)[_i]), (PG8_LAS unsigned*)(lds + (bufoff) + ldsw + _i * 8192), 16, 0, 0); } while (0)
; #define PG8_LDA(dst, b, h) do { _Pragma("unroll") for (int m = 0; m < 4; ++m) _Pragma("unroll") for (int k = 0; k < 2; ++k) dst[m][k] = *(const PG8_LAS bf16x8*)(lds + PG8_SA(b, h) + aoff + m * 2048 + k * 1024); } while (0)
; #define PG8_LDB(dst, b, h) do { _Pragma("unroll") for (int n = 0; n < 2; ++n) _Pragma("unroll") for (int k = 0; k < 2; ++k) dst[n][k] = *(const PG8_LAS bf16x8*)(lds + PG8_SB(b, h) + boff + n * 2048 + k * 1024); } while (0)
; #define PG8_MMA(ai, bj, At, Bt) do { __builtin_amdgcn_s_setprio(1); _Pragma("unroll") for (int m = 0; m < 4; ++m) _Pragma("unroll") for (int n = 0; n < 2; ++n) _Pragma("unroll") for (int k = 0; k < 2; ++k) \
;         acc[ai][bj][m][n] = __builtin_amdgcn_mfma_f32_16x16x32_bf16(Bt[n][k], At[m][k], acc[ai][bj][m][n], 0, 0, 0); __builtin_amdgcn_s_setprio(0); } while (0)
; #define PG8_WAIT_V(n) asm volatile("s_waitcnt vmcnt(" #n ")" ::: "memory")
; #define PG8_WAIT_L(n) asm volatile("s_waitcnt lgkmcnt(" #n ")" ::: "memory")
; #define PG8_BAR __builtin_amdgcn_s_barrier()
; #define PG8_SCHED __builtin_amdgcn_sched_barrier(0)
; template <class Epi, class Sched, bool ALIGN_EPI = false, bool SP2 = false>
; __device__ __forceinline__ void gemm_phase(PG8_LAS unsigned char* lds, const Gemm g, const Sched& S, const Epi& E, int tid_in) {
;     ...
;             PG8_WAIT_V(8); PG8_WAIT_L(0); PG8_BAR; PG8_MMA(1, 0, At, B0); PG8_MMA(1, 1, At, B1); PG8_BAR; PG8_SCHED;
;             PG8_LDB(B0, 1, 0); PG8_LDB(B1, 1, 1); PG8_SCHED; PG8_LDA(At, 1, 0); PG8_STAGE(PG8_SA(0, 1), a2 + hstep, voffA);
;             PG8_WAIT_V(8); PG8_WAIT_L(0); PG8_BAR; PG8_MMA(0, 0, At, B0); PG8_MMA(0, 1, At, B1); PG8_BAR; PG8_SCHED;
;             PG8_LDA(At, 1, 1); PG8_STAGE(PG8_SB(1, 0), b3, voffB); PG8_STAGE(PG8_SB(1, 1), b3 + hstep, voffB); PG8_STAGE(PG8_SA(1, 0), a3, voffA);
;             PG8_WAIT_V(8); PG8_WAIT_L(0); PG8_BAR; PG8_MMA(1, 0, At, B0); PG8_MMA(1, 1, At, B1); PG8_BAR; PG8_SCHED;
	v_mfma_f32_16x16x32_bf16 v[60:63], v[144:147], v[186:189], 0
	v_mfma_f32_16x16x32_bf16 v[56:59], v[162:165], v[186:189], 0
	v_mfma_f32_16x16x32_bf16 v[44:47], v[144:147], v[194:197], 0
	v_mfma_f32_16x16x32_bf16 v[40:43], v[162:165], v[194:197], 0
	v_mfma_f32_16x16x32_bf16 v[28:31], v[144:147], v[202:205], 0
	v_mfma_f32_16x16x32_bf16 v[24:27], v[162:165], v[202:205], 0
	v_mfma_f32_16x16x32_bf16 v[12:15], v[144:147], v[210:213], 0
	v_mfma_f32_16x16x32_bf16 v[8:11], v[162:165], v[210:213], 0
	v_mfma_f32_16x16x32_bf16 v[60:63], v[158:161], v[190:193], v[60:63]
	v_mfma_f32_16x16x32_bf16 v[56:59], v[166:169], v[190:193], v[56:59]
	v_mfma_f32_16x16x32_bf16 v[44:47], v[158:161], v[198:201], v[44:47]
	v_mfma_f32_16x16x32_bf16 v[40:43], v[166:169], v[198:201], v[40:43]
	v_mfma_f32_16x16x32_bf16 v[28:31], v[158:161], v[206:209], v[28:31]
	v_mfma_f32_16x16x32_bf16 v[24:27], v[166:169], v[206:209], v[24:27]
	v_mfma_f32_16x16x32_bf16 v[12:15], v[158:161], v[214:217], v[12:15]
	v_mfma_f32_16x16x32_bf16 v[8:11], v[166:169], v[214:217], v[8:11]
	v_mfma_f32_16x16x32_bf16 v[52:55], v[170:173], v[186:189], 0
	v_mfma_f32_16x16x32_bf16 v[48:51], v[178:181], v[186:189], 0
	v_mfma_f32_16x16x32_bf16 v[36:39], v[170:173], v[194:197], 0
	v_mfma_f32_16x16x32_bf16 v[32:35], v[178:181], v[194:197], 0
	v_mfma_f32_16x16x32_bf16 v[20:23], v[170:173], v[202:205], 0
	v_mfma_f32_16x16x32_bf16 v[16:19], v[178:181], v[202:205], 0
	v_mfma_f32_16x16x32_bf16 v[4:7], v[170:173], v[210:213], 0
	v_mfma_f32_16x16x32_bf16 v[0:3], v[178:181], v[210:213], 0
	v_mfma_f32_16x16x32_bf16 v[52:55], v[174:177], v[190:193], v[52:55]
	v_mfma_f32_16x16x32_bf16 v[48:51], v[182:185], v[190:193], v[48:51]
	v_mfma_f32_16x16x32_bf16 v[36:39], v[174:177], v[198:201], v[36:39]
	v_mfma_f32_16x16x32_bf16 v[32:35], v[182:185], v[198:201], v[32:35]
	v_mfma_f32_16x16x32_bf16 v[20:23], v[174:177], v[206:209], v[20:23]
	v_mfma_f32_16x16x32_bf16 v[16:19], v[182:185], v[206:209], v[16:19]
	v_mfma_f32_16x16x32_bf16 v[4:7], v[174:177], v[214:217], v[4:7]
	v_mfma_f32_16x16x32_bf16 v[0:3], v[182:185], v[214:217], v[0:3]
	s_barrier
	s_add_i32 s59, 0, 0x18000
	s_add_i32 s60, 0, 0x1c000
	s_add_u32 s28, s28, 0x40000
	s_addc_u32 s29, s29, 0
	s_mov_b32 m0, s38
	v_add_u32_e32 v157, s59, v151
	global_load_lds_dwordx4 v134, s[28:29]
	s_mov_b32 m0, s39
	ds_read_b128 v[144:147], v157
	global_load_lds_dwordx4 v130, s[28:29]
	ds_read_b128 v[158:161], v157 offset:1024
	ds_read_b128 v[162:165], v157 offset:2048
	ds_read_b128 v[166:169], v157 offset:3072
	v_add_u32_e32 v157, s60, v151
	ds_read_b128 v[170:173], v157
	ds_read_b128 v[174:177], v157 offset:1024
	ds_read_b128 v[178:181], v157 offset:2048
	ds_read_b128 v[182:185], v157 offset:3072
	ds_read_b128 v[186:189], v156 offset:32768
	ds_read_b128 v[190:193], v156 offset:33792
	ds_read_b128 v[194:197], v156 offset:34816
	ds_read_b128 v[198:201], v156 offset:35840
	ds_read_b128 v[202:205], v156 offset:36864
	ds_read_b128 v[206:209], v156 offset:37888
	ds_read_b128 v[210:213], v156 offset:38912
	ds_read_b128 v[214:217], v156 offset:39936
	s_waitcnt vmcnt(8)
	s_waitcnt lgkmcnt(0)
	s_barrier
	v_mfma_f32_16x16x32_bf16 v[124:127], v[144:147], v[186:189], v[124:127]
	v_mfma_f32_16x16x32_bf16 v[120:123], v[162:165], v[186:189], v[120:123]
	v_mfma_f32_16x16x32_bf16 v[108:111], v[144:147], v[194:197], v[108:111]
	v_mfma_f32_16x16x32_bf16 v[104:107], v[162:165], v[194:197], v[104:107]
	v_mfma_f32_16x16x32_bf16 v[92:95], v[144:147], v[202:205], v[92:95]
	v_mfma_f32_16x16x32_bf16 v[88:91], v[162:165], v[202:205], v[88:91]
	v_mfma_f32_16x16x32_bf16 v[76:79], v[144:147], v[210:213], v[76:79]
	v_mfma_f32_16x16x32_bf16 v[72:75], v[162:165], v[210:213], v[72:75]
	v_mfma_f32_16x16x32_bf16 v[124:127], v[158:161], v[190:193], v[124:127]
	v_mfma_f32_16x16x32_bf16 v[120:123], v[166:169], v[190:193], v[120:123]
	v_mfma_f32_16x16x32_bf16 v[108:111], v[158:161], v[198:201], v[108:111]
	v_mfma_f32_16x16x32_bf16 v[104:107], v[166:169], v[198:201], v[104:107]
	v_mfma_f32_16x16x32_bf16 v[92:95], v[158:161], v[206:209], v[92:95]
	v_mfma_f32_16x16x32_bf16 v[88:91], v[166:169], v[206:209], v[88:91]
	v_mfma_f32_16x16x32_bf16 v[76:79], v[158:161], v[214:217], v[76:79]
	v_mfma_f32_16x16x32_bf16 v[72:75], v[166:169], v[214:217], v[72:75]
	v_mfma_f32_16x16x32_bf16 v[116:119], v[170:173], v[186:189], v[116:119]
	v_mfma_f32_16x16x32_bf16 v[112:115], v[178:181], v[186:189], v[112:115]
	v_mfma_f32_16x16x32_bf16 v[100:103], v[170:173], v[194:197], v[100:103]
	v_mfma_f32_16x16x32_bf16 v[96:99], v[178:181], v[194:197], v[96:99]
	v_mfma_f32_16x16x32_bf16 v[84:87], v[170:173], v[202:205], v[84:87]
	v_mfma_f32_16x16x32_bf16 v[80:83], v[178:181], v[202:205], v[80:83]
	v_mfma_f32_16x16x32_bf16 v[68:71], v[170:173], v[210:213], v[68:71]
	v_mfma_f32_16x16x32_bf16 v[64:67], v[178:181], v[210:213], v[64:67]
	v_mfma_f32_16x16x32_bf16 v[116:119], v[174:177], v[190:193], v[116:119]
	v_mfma_f32_16x16x32_bf16 v[112:115], v[182:185], v[190:193], v[112:115]
	v_mfma_f32_16x16x32_bf16 v[100:103], v[174:177], v[198:201], v[100:103]
	v_mfma_f32_16x16x32_bf16 v[96:99], v[182:185], v[198:201], v[96:99]
	v_mfma_f32_16x16x32_bf16 v[84:87], v[174:177], v[206:209], v[84:87]
	v_mfma_f32_16x16x32_bf16 v[80:83], v[182:185], v[206:209], v[80:83]
	v_mfma_f32_16x16x32_bf16 v[68:71], v[174:177], v[214:217], v[68:71]
	v_mfma_f32_16x16x32_bf16 v[64:67], v[182:185], v[214:217], v[64:67]
	s_barrier
; #define PG8_STAGE(bufoff, gbase, voff) do { _Pragma("unroll") for (int _i = 0; _i < 2; ++_i) \
;         __builtin_amdgcn_global_load_lds((const unsigned*)((const char*)(gbase) + (voff)[_i]), (PG8_LAS unsigned*)(lds + (bufoff) + ldsw + _i * 8192), 16, 0, 0); } while (0)
; #define PG8_LDA(dst, b, h) do { _Pragma("unroll") for (int m = 0; m < 4; ++m) _Pragma("unroll") for (int k = 0; k < 2; ++k) dst[m][k] = *(const PG8_LAS bf16x8*)(lds + PG8_SA(b, h) + aoff + m * 2048 + k * 1024); } while (0)
; #define PG8_MMA(ai, bj, At, Bt) do { __builtin_amdgcn_s_setprio(1); _Pragma("unroll") for (int m = 0; m < 4; ++m) _Pragma("unroll") for (int n = 0; n < 2; ++n) _Pragma("unroll") for (int k = 0; k < 2; ++k) \
;         acc[ai][bj][m][n] = __builtin_amdgcn_mfma_f32_16x16x32_bf16(Bt[n][k], At[m][k], acc[ai][bj][m][n], 0, 0, 0); __builtin_amdgcn_s_setprio(0); } while (0)
; #define PG8_WAIT_V(n) asm volatile("s_waitcnt vmcnt(" #n ")" ::: "memory")
; #define PG8_WAIT_L(n) asm volatile("s_waitcnt lgkmcnt(" #n ")" ::: "memory")
; #define PG8_BAR __builtin_amdgcn_s_barrier()
; #define PG8_SCHED __builtin_amdgcn_sched_barrier(0)
; template <class Epi, class Sched, bool ALIGN_EPI = false, bool SP2 = false>
; __device__ __forceinline__ void gemm_phase(PG8_LAS unsigned char* lds, const Gemm g, const Sched& S, const Epi& E, int tid_in) {
;     ...
;             PG8_LDA(At, 1, 1); PG8_STAGE(PG8_SB(1, 0), b3, voffB); PG8_STAGE(PG8_SB(1, 1), b3 + hstep, voffB); PG8_STAGE(PG8_SA(1, 0), a3, voffA);
;             PG8_WAIT_V(8); PG8_WAIT_L(0); PG8_BAR; PG8_MMA(1, 0, At, B0); PG8_MMA(1, 1, At, B1); PG8_BAR; PG8_SCHED;
	s_add_i32 s28, s59, s0
	s_mov_b32 m0, s28
	ds_read_b128 v[186:189], v156 offset:49152
	global_load_lds_dwordx4 v132, s[98:99]
	s_add_i32 m0, s28, 0x2000
	s_add_u32 s26, s26, 0x40080
	s_addc_u32 s27, s27, 0
	s_add_i32 s28, s60, s0
	global_load_lds_dwordx4 v128, s[98:99]
	s_mov_b32 m0, s28
	ds_read_b128 v[190:193], v156 offset:50176
	global_load_lds_dwordx4 v132, s[26:27]
	s_add_i32 m0, s28, 0x2000
	ds_read_b128 v[194:197], v156 offset:51200
	global_load_lds_dwordx4 v128, s[26:27]
	s_mov_b32 m0, s44
	ds_read_b128 v[198:201], v156 offset:52224
	global_load_lds_dwordx4 v134, s[100:101]
	s_mov_b32 m0, s45
	ds_read_b128 v[202:205], v156 offset:53248
	global_load_lds_dwordx4 v130, s[100:101]
	ds_read_b128 v[206:209], v156 offset:54272
	ds_read_b128 v[210:213], v156 offset:55296
	ds_read_b128 v[214:217], v156 offset:56320
	s_waitcnt vmcnt(8)
	s_waitcnt lgkmcnt(0)
	s_barrier
	v_mfma_f32_16x16x32_bf16 v[60:63], v[144:147], v[186:189], v[60:63]
	v_mfma_f32_16x16x32_bf16 v[56:59], v[162:165], v[186:189], v[56:59]
	v_mfma_f32_16x16x32_bf16 v[44:47], v[144:147], v[194:197], v[44:47]
	v_mfma_f32_16x16x32_bf16 v[40:43], v[162:165], v[194:197], v[40:43]
	v_mfma_f32_16x16x32_bf16 v[28:31], v[144:147], v[202:205], v[28:31]
	v_mfma_f32_16x16x32_bf16 v[24:27], v[162:165], v[202:205], v[24:27]
	v_mfma_f32_16x16x32_bf16 v[12:15], v[144:147], v[210:213], v[12:15]
	v_mfma_f32_16x16x32_bf16 v[8:11], v[162:165], v[210:213], v[8:11]
	v_mfma_f32_16x16x32_bf16 v[60:63], v[158:161], v[190:193], v[60:63]
	v_mfma_f32_16x16x32_bf16 v[56:59], v[166:169], v[190:193], v[56:59]
	v_mfma_f32_16x16x32_bf16 v[44:47], v[158:161], v[198:201], v[44:47]
	v_mfma_f32_16x16x32_bf16 v[40:43], v[166:169], v[198:201], v[40:43]
	v_mfma_f32_16x16x32_bf16 v[28:31], v[158:161], v[206:209], v[28:31]
	v_mfma_f32_16x16x32_bf16 v[24:27], v[166:169], v[206:209], v[24:27]
	v_mfma_f32_16x16x32_bf16 v[12:15], v[158:161], v[214:217], v[12:15]
	v_mfma_f32_16x16x32_bf16 v[8:11], v[166:169], v[214:217], v[8:11]
	v_mfma_f32_16x16x32_bf16 v[52:55], v[170:173], v[186:189], v[52:55]
	v_mfma_f32_16x16x32_bf16 v[48:51], v[178:181], v[186:189], v[48:51]
	v_mfma_f32_16x16x32_bf16 v[36:39], v[170:173], v[194:197], v[36:39]
	v_mfma_f32_16x16x32_bf16 v[32:35], v[178:181], v[194:197], v[32:35]
	v_mfma_f32_16x16x32_bf16 v[20:23], v[170:173], v[202:205], v[20:23]
	v_mfma_f32_16x16x32_bf16 v[16:19], v[178:181], v[202:205], v[16:19]
	v_mfma_f32_16x16x32_bf16 v[4:7], v[170:173], v[210:213], v[4:7]
	v_mfma_f32_16x16x32_bf16 v[0:3], v[178:181], v[210:213], v[0:3]
	v_mfma_f32_16x16x32_bf16 v[52:55], v[174:177], v[190:193], v[52:55]
	v_mfma_f32_16x16x32_bf16 v[48:51], v[182:185], v[190:193], v[48:51]
	v_mfma_f32_16x16x32_bf16 v[36:39], v[174:177], v[198:201], v[36:39]
	v_mfma_f32_16x16x32_bf16 v[32:35], v[182:185], v[198:201], v[32:35]
	v_mfma_f32_16x16x32_bf16 v[20:23], v[174:177], v[206:209], v[20:23]
	v_mfma_f32_16x16x32_bf16 v[16:19], v[182:185], v[206:209], v[16:19]
	v_mfma_f32_16x16x32_bf16 v[4:7], v[174:177], v[214:217], v[4:7]
	v_mfma_f32_16x16x32_bf16 v[0:3], v[182:185], v[214:217], v[0:3]
	s_barrier
	s_add_i32 s58, s58, 2
	s_add_u32 s24, s24, 0x100
	s_addc_u32 s25, s25, 0
	s_add_u32 s56, s56, 0x100
	s_addc_u32 s57, s57, 0

; #define PG8_STAGE(bufoff, gbase, voff) do { _Pragma("unroll") for (int _i = 0; _i < 2; ++_i) \
;         __builtin_amdgcn_global_load_lds((const unsigned*)((const char*)(gbase) + (voff)[_i]), (PG8_LAS unsigned*)(lds + (bufoff) + ldsw + _i * 8192), 16, 0, 0); } while (0)
; #define PG8_LDA(dst, b, h) do { _Pragma("unroll") for (int m = 0; m < 4; ++m) _Pragma("unroll") for (int k = 0; k < 2; ++k) dst[m][k] = *(const PG8_LAS bf16x8*)(lds + PG8_SA(b, h) + aoff + m * 2048 + k * 1024); } while (0)
; #define PG8_LDB(dst, b, h) do { _Pragma("unroll") for (int n = 0; n < 2; ++n) _Pragma("unroll") for (int k = 0; k < 2; ++k) dst[n][k] = *(const PG8_LAS bf16x8*)(lds + PG8_SB(b, h) + boff + n * 2048 + k * 1024); } while (0)
; #define PG8_MMA(ai, bj, At, Bt) do { __builtin_amdgcn_s_setprio(1); _Pragma("unroll") for (int m = 0; m < 4; ++m) _Pragma("unroll") for (int n = 0; n < 2; ++n) _Pragma("unroll") for (int k = 0; k < 2; ++k) \
;         acc[ai][bj][m][n] = __builtin_amdgcn_mfma_f32_16x16x32_bf16(Bt[n][k], At[m][k], acc[ai][bj][m][n], 0, 0, 0); __builtin_amdgcn_s_setprio(0); } while (0)
; #define PG8_WAIT_V(n) asm volatile("s_waitcnt vmcnt(" #n ")" ::: "memory")
; #define PG8_WAIT_L(n) asm volatile("s_waitcnt lgkmcnt(" #n ")" ::: "memory")
; #define PG8_BAR __builtin_amdgcn_s_barrier()
; #define PG8_SCHED __builtin_amdgcn_sched_barrier(0)
; template <class Epi, class Sched, bool ALIGN_EPI = false, bool SP2 = false>
; __device__ __forceinline__ void gemm_phase(PG8_LAS unsigned char* lds, const Gemm g, const Sched& S, const Epi& E, int tid_in) {
;     ...
;             const char* a2 = last ? nA : cA + (size_t)(t + 2) * kstep; const char* b2 = last ? nB : cB + (size_t)(t + 2) * kstep;
;             const char* a3 = a2 + kstep; const char* b3 = b2 + kstep;
;             if (last && has_next) S.a_ready(nxt);
;             if constexpr (SP2) {
;             PG8_LDB(B0, 0, 0); PG8_LDB(B1, 0, 1); PG8_SCHED; PG8_LDA(At, 0, 0); PG8_STAGE(PG8_SA(1, 1), a1 + hstep, voffA);
;             PG8_WAIT_V(8); PG8_WAIT_L(0); PG8_BAR; PG8_MMA(0, 0, At, B0); PG8_MMA(0, 1, At, B1); PG8_BAR; PG8_SCHED;
;             PG8_LDA(At, 0, 1); PG8_STAGE(PG8_SB(0, 0), b2, voffB); PG8_STAGE(PG8_SB(0, 1), b2 + hstep, voffB); PG8_STAGE(PG8_SA(0, 0), a2, voffA);
;             PG8_WAIT_V(8); PG8_WAIT_L(0); PG8_BAR; PG8_MMA(1, 0, At, B0); PG8_MMA(1, 1, At, B1); PG8_BAR; PG8_SCHED;
.LBB0_1320:
	s_add_u32 s48, s22, 0x100
	s_addc_u32 s49, s23, 0
	s_mov_b32 s50, -2
	s_waitcnt vmcnt(0)
	s_add_u32 s2, s20, 0x100
	s_addc_u32 s3, s21, 0
	s_cmp_eq_u32 s50, 40
	s_cselect_b32 s25, s17, s3
	s_cselect_b32 s24, s16, s2
	s_cselect_b32 s23, s19, s49
	s_cselect_b32 s22, s18, s48
	s_add_i32 m0, s34, 0xc000
	ds_read_b128 v[128:131], v195
	global_load_lds_dwordx4 v168, s[20:21]
	s_add_i32 m0, s34, 0xe000
	ds_read_b128 v[132:135], v195 offset:1024
	global_load_lds_dwordx4 v170, s[20:21]
	ds_read_b128 v[136:139], v195 offset:2048
	ds_read_b128 v[140:143], v195 offset:3072
	ds_read_b128 v[144:147], v196
	ds_read_b128 v[148:151], v196 offset:1024
	ds_read_b128 v[152:155], v196 offset:2048
	ds_read_b128 v[156:159], v196 offset:3072
	ds_read_b128 v[176:179], v197
	ds_read_b128 v[180:183], v197 offset:1024
	ds_read_b128 v[184:187], v197 offset:2048
	ds_read_b128 v[188:191], v197 offset:3072
	ds_read_b128 v[198:201], v197 offset:4096
	ds_read_b128 v[202:205], v197 offset:5120
	ds_read_b128 v[206:209], v197 offset:6144
	ds_read_b128 v[210:213], v197 offset:7168
	s_waitcnt vmcnt(8)
	s_waitcnt lgkmcnt(0)
	s_barrier
	v_mfma_f32_16x16x32_bf16 v[120:123], v[128:131], v[176:179], 0
	v_mfma_f32_16x16x32_bf16 v[124:127], v[136:139], v[176:179], 0
	v_mfma_f32_16x16x32_bf16 v[104:107], v[128:131], v[184:187], 0
	v_mfma_f32_16x16x32_bf16 v[108:111], v[136:139], v[184:187], 0
	v_mfma_f32_16x16x32_bf16 v[88:91], v[128:131], v[198:201], 0
	v_mfma_f32_16x16x32_bf16 v[92:95], v[136:139], v[198:201], 0
	v_mfma_f32_16x16x32_bf16 v[72:75], v[128:131], v[206:209], 0
	v_mfma_f32_16x16x32_bf16 v[76:79], v[136:139], v[206:209], 0
	v_mfma_f32_16x16x32_bf16 v[120:123], v[132:135], v[180:183], v[120:123]
	v_mfma_f32_16x16x32_bf16 v[124:127], v[140:143], v[180:183], v[124:127]
	v_mfma_f32_16x16x32_bf16 v[104:107], v[132:135], v[188:191], v[104:107]
	v_mfma_f32_16x16x32_bf16 v[108:111], v[140:143], v[188:191], v[108:111]
	v_mfma_f32_16x16x32_bf16 v[88:91], v[132:135], v[202:205], v[88:91]
	v_mfma_f32_16x16x32_bf16 v[92:95], v[140:143], v[202:205], v[92:95]
	v_mfma_f32_16x16x32_bf16 v[72:75], v[132:135], v[210:213], v[72:75]
	v_mfma_f32_16x16x32_bf16 v[76:79], v[140:143], v[210:213], v[76:79]
	v_mfma_f32_16x16x32_bf16 v[112:115], v[144:147], v[176:179], 0
	v_mfma_f32_16x16x32_bf16 v[116:119], v[152:155], v[176:179], 0
	v_mfma_f32_16x16x32_bf16 v[96:99], v[144:147], v[184:187], 0
	v_mfma_f32_16x16x32_bf16 v[100:103], v[152:155], v[184:187], 0
	v_mfma_f32_16x16x32_bf16 v[80:83], v[144:147], v[198:201], 0
	v_mfma_f32_16x16x32_bf16 v[84:87], v[152:155], v[198:201], 0
	v_mfma_f32_16x16x32_bf16 v[64:67], v[144:147], v[206:209], 0
	v_mfma_f32_16x16x32_bf16 v[68:71], v[152:155], v[206:209], 0
	v_mfma_f32_16x16x32_bf16 v[112:115], v[148:151], v[180:183], v[112:115]
	v_mfma_f32_16x16x32_bf16 v[116:119], v[156:159], v[180:183], v[116:119]
	v_mfma_f32_16x16x32_bf16 v[96:99], v[148:151], v[188:191], v[96:99]
	v_mfma_f32_16x16x32_bf16 v[100:103], v[156:159], v[188:191], v[100:103]
	v_mfma_f32_16x16x32_bf16 v[80:83], v[148:151], v[202:205], v[80:83]
	v_mfma_f32_16x16x32_bf16 v[84:87], v[156:159], v[202:205], v[84:87]
	v_mfma_f32_16x16x32_bf16 v[64:67], v[148:151], v[210:213], v[64:67]
	v_mfma_f32_16x16x32_bf16 v[68:71], v[156:159], v[210:213], v[68:71]
	s_barrier
	s_add_u32 s98, s22, s10
	s_addc_u32 s99, s23, s11
	s_add_u32 s100, s24, s10
	s_addc_u32 s101, s25, s11
	s_add_i32 s20, s42, s31
	s_mov_b32 m0, s20
	ds_read_b128 v[176:179], v197 offset:16384
	global_load_lds_dwordx4 v162, s[22:23]
	s_add_i32 m0, s20, 0x2000
	s_add_u32 s20, s22, 0xb0000
	s_addc_u32 s21, s23, 0
	s_add_i32 s51, s43, s31
	global_load_lds_dwordx4 v166, s[22:23]
	s_mov_b32 m0, s51
	ds_read_b128 v[180:183], v197 offset:17408
	global_load_lds_dwordx4 v162, s[20:21]
	s_add_i32 m0, s51, 0x2000
	ds_read_b128 v[184:187], v197 offset:18432
	global_load_lds_dwordx4 v166, s[20:21]
	s_mov_b32 m0, s34
	ds_read_b128 v[188:191], v197 offset:19456
	global_load_lds_dwordx4 v160, s[24:25]
	s_mov_b32 m0, s35
	ds_read_b128 v[198:201], v197 offset:20480
	global_load_lds_dwordx4 v164, s[24:25]
	ds_read_b128 v[202:205], v197 offset:21504
	ds_read_b128 v[206:209], v197 offset:22528
	ds_read_b128 v[210:213], v197 offset:23552
	s_waitcnt vmcnt(8)
	s_waitcnt lgkmcnt(0)
	s_barrier
	v_mfma_f32_16x16x32_bf16 v[56:59], v[128:131], v[176:179], 0
	v_mfma_f32_16x16x32_bf16 v[60:63], v[136:139], v[176:179], 0
	v_mfma_f32_16x16x32_bf16 v[40:43], v[128:131], v[184:187], 0
	v_mfma_f32_16x16x32_bf16 v[44:47], v[136:139], v[184:187], 0
	v_mfma_f32_16x16x32_bf16 v[24:27], v[128:131], v[198:201], 0
	v_mfma_f32_16x16x32_bf16 v[28:31], v[136:139], v[198:201], 0
	v_mfma_f32_16x16x32_bf16 v[8:11], v[128:131], v[206:209], 0
	v_mfma_f32_16x16x32_bf16 v[12:15], v[136:139], v[206:209], 0
	v_mfma_f32_16x16x32_bf16 v[56:59], v[132:135], v[180:183], v[56:59]
	v_mfma_f32_16x16x32_bf16 v[60:63], v[140:143], v[180:183], v[60:63]
	v_mfma_f32_16x16x32_bf16 v[40:43], v[132:135], v[188:191], v[40:43]
	v_mfma_f32_16x16x32_bf16 v[44:47], v[140:143], v[188:191], v[44:47]
	v_mfma_f32_16x16x32_bf16 v[24:27], v[132:135], v[202:205], v[24:27]
	v_mfma_f32_16x16x32_bf16 v[28:31], v[140:143], v[202:205], v[28:31]
	v_mfma_f32_16x16x32_bf16 v[8:11], v[132:135], v[210:213], v[8:11]
	v_mfma_f32_16x16x32_bf16 v[12:15], v[140:143], v[210:213], v[12:15]
	v_mfma_f32_16x16x32_bf16 v[48:51], v[144:147], v[176:179], 0
	v_mfma_f32_16x16x32_bf16 v[52:55], v[152:155], v[176:179], 0
	v_mfma_f32_16x16x32_bf16 v[32:35], v[144:147], v[184:187], 0
	v_mfma_f32_16x16x32_bf16 v[36:39], v[152:155], v[184:187], 0
	v_mfma_f32_16x16x32_bf16 v[16:19], v[144:147], v[198:201], 0
	v_mfma_f32_16x16x32_bf16 v[20:23], v[152:155], v[198:201], 0
	v_mfma_f32_16x16x32_bf16 v[4:7], v[144:147], v[206:209], 0
	v_mfma_f32_16x16x32_bf16 v[0:3], v[152:155], v[206:209], 0
	v_mfma_f32_16x16x32_bf16 v[48:51], v[148:151], v[180:183], v[48:51]
	v_mfma_f32_16x16x32_bf16 v[52:55], v[156:159], v[180:183], v[52:55]
	v_mfma_f32_16x16x32_bf16 v[32:35], v[148:151], v[188:191], v[32:35]
	v_mfma_f32_16x16x32_bf16 v[36:39], v[156:159], v[188:191], v[36:39]
	v_mfma_f32_16x16x32_bf16 v[16:19], v[148:151], v[202:205], v[16:19]
	v_mfma_f32_16x16x32_bf16 v[20:23], v[156:159], v[202:205], v[20:23]
	v_mfma_f32_16x16x32_bf16 v[4:7], v[148:151], v[210:213], v[4:7]
	v_mfma_f32_16x16x32_bf16 v[0:3], v[156:159], v[210:213], v[0:3]
	s_barrier
; #define PG8_STAGE(bufoff, gbase, voff) do { _Pragma("unroll") for (int _i = 0; _i < 2; ++_i) \
;         __builtin_amdgcn_global_load_lds((const unsigned*)((const char*)(gbase) + (voff)[_i]), (PG8_LAS unsigned*)(lds + (bufoff) + ldsw + _i * 8192), 16, 0, 0); } while (0)
; #define PG8_LDA(dst, b, h) do { _Pragma("unroll") for (int m = 0; m < 4; ++m) _Pragma("unroll") for (int k = 0; k < 2; ++k) dst[m][k] = *(const PG8_LAS bf16x8*)(lds + PG8_SA(b, h) + aoff + m * 2048 + k * 1024); } while (0)
; #define PG8_LDB(dst, b, h) do { _Pragma("unroll") for (int n = 0; n < 2; ++n) _Pragma("unroll") for (int k = 0; k < 2; ++k) dst[n][k] = *(const PG8_LAS bf16x8*)(lds + PG8_SB(b, h) + boff + n * 2048 + k * 1024); } while (0)
; #define PG8_MMA(ai, bj, At, Bt) do { __builtin_amdgcn_s_setprio(1); _Pragma("unroll") for (int m = 0; m < 4; ++m) _Pragma("unroll") for (int n = 0; n < 2; ++n) _Pragma("unroll") for (int k = 0; k < 2; ++k) \
;         acc[ai][bj][m][n] = __builtin_amdgcn_mfma_f32_16x16x32_bf16(Bt[n][k], At[m][k], acc[ai][bj][m][n], 0, 0, 0); __builtin_amdgcn_s_setprio(0); } while (0)
; #define PG8_WAIT_V(n) asm volatile("s_waitcnt vmcnt(" #n ")" ::: "memory")
; #define PG8_WAIT_L(n) asm volatile("s_waitcnt lgkmcnt(" #n ")" ::: "memory")
; #define PG8_BAR __builtin_amdgcn_s_barrier()
; #define PG8_SCHED __builtin_amdgcn_sched_barrier(0)
; template <class Epi, class Sched, bool ALIGN_EPI = false, bool SP2 = false>
; __device__ __forceinline__ void gemm_phase(PG8_LAS unsigned char* lds, const Gemm g, const Sched& S, const Epi& E, int tid_in) {
;     ...
;             PG8_LDB(B0, 1, 0); PG8_LDB(B1, 1, 1); PG8_SCHED; PG8_LDA(At, 1, 0); PG8_STAGE(PG8_SA(0, 1), a2 + hstep, voffA);
;             PG8_WAIT_V(8); PG8_WAIT_L(0); PG8_BAR; PG8_MMA(0, 0, At, B0); PG8_MMA(0, 1, At, B1); PG8_BAR; PG8_SCHED;
;             PG8_LDA(At, 1, 1); PG8_STAGE(PG8_SB(1, 0), b3, voffB); PG8_STAGE(PG8_SB(1, 1), b3 + hstep, voffB); PG8_STAGE(PG8_SA(1, 0), a3, voffA);
;             PG8_WAIT_V(8); PG8_WAIT_L(0); PG8_BAR; PG8_MMA(1, 0, At, B0); PG8_MMA(1, 1, At, B1); PG8_BAR; PG8_SCHED;
	s_add_i32 s51, 0, 0x18000
	s_add_i32 s52, 0, 0x1c000
	s_add_u32 s20, s24, 0xb0000
	s_addc_u32 s21, s25, 0
	s_mov_b32 m0, s36
	s_nop 0
	global_load_lds_dwordx4 v160, s[20:21]
	s_mov_b32 m0, s37
	s_nop 0
	global_load_lds_dwordx4 v164, s[20:21]
	v_add_u32_e32 v140, s51, v193
	v_add_u32_e32 v156, s52, v193
	ds_read_b128 v[128:131], v140
	ds_read_b128 v[132:135], v140 offset:1024
	ds_read_b128 v[136:139], v140 offset:2048
	ds_read_b128 v[140:143], v140 offset:3072
	ds_read_b128 v[144:147], v156
	ds_read_b128 v[148:151], v156 offset:1024
	ds_read_b128 v[152:155], v156 offset:2048
	ds_read_b128 v[156:159], v156 offset:3072
	ds_read_b128 v[176:179], v197 offset:32768
	ds_read_b128 v[180:183], v197 offset:33792
	ds_read_b128 v[184:187], v197 offset:34816
	ds_read_b128 v[188:191], v197 offset:35840
	ds_read_b128 v[198:201], v197 offset:36864
	ds_read_b128 v[202:205], v197 offset:37888
	ds_read_b128 v[206:209], v197 offset:38912
	ds_read_b128 v[210:213], v197 offset:39936
	s_waitcnt vmcnt(8)
	s_waitcnt lgkmcnt(0)
	s_barrier
	v_mfma_f32_16x16x32_bf16 v[120:123], v[128:131], v[176:179], v[120:123]
	v_mfma_f32_16x16x32_bf16 v[124:127], v[136:139], v[176:179], v[124:127]
	v_mfma_f32_16x16x32_bf16 v[104:107], v[128:131], v[184:187], v[104:107]
	v_mfma_f32_16x16x32_bf16 v[108:111], v[136:139], v[184:187], v[108:111]
	v_mfma_f32_16x16x32_bf16 v[88:91], v[128:131], v[198:201], v[88:91]
	v_mfma_f32_16x16x32_bf16 v[92:95], v[136:139], v[198:201], v[92:95]
	v_mfma_f32_16x16x32_bf16 v[72:75], v[128:131], v[206:209], v[72:75]
	v_mfma_f32_16x16x32_bf16 v[76:79], v[136:139], v[206:209], v[76:79]
	v_mfma_f32_16x16x32_bf16 v[120:123], v[132:135], v[180:183], v[120:123]
	v_mfma_f32_16x16x32_bf16 v[124:127], v[140:143], v[180:183], v[124:127]
	v_mfma_f32_16x16x32_bf16 v[104:107], v[132:135], v[188:191], v[104:107]
	v_mfma_f32_16x16x32_bf16 v[108:111], v[140:143], v[188:191], v[108:111]
	v_mfma_f32_16x16x32_bf16 v[88:91], v[132:135], v[202:205], v[88:91]
	v_mfma_f32_16x16x32_bf16 v[92:95], v[140:143], v[202:205], v[92:95]
	v_mfma_f32_16x16x32_bf16 v[72:75], v[132:135], v[210:213], v[72:75]
	v_mfma_f32_16x16x32_bf16 v[76:79], v[140:143], v[210:213], v[76:79]
	v_mfma_f32_16x16x32_bf16 v[112:115], v[144:147], v[176:179], v[112:115]
	v_mfma_f32_16x16x32_bf16 v[116:119], v[152:155], v[176:179], v[116:119]
	v_mfma_f32_16x16x32_bf16 v[96:99], v[144:147], v[184:187], v[96:99]
	v_mfma_f32_16x16x32_bf16 v[100:103], v[152:155], v[184:187], v[100:103]
	v_mfma_f32_16x16x32_bf16 v[80:83], v[144:147], v[198:201], v[80:83]
	v_mfma_f32_16x16x32_bf16 v[84:87], v[152:155], v[198:201], v[84:87]
	v_mfma_f32_16x16x32_bf16 v[64:67], v[144:147], v[206:209], v[64:67]
	v_mfma_f32_16x16x32_bf16 v[68:71], v[152:155], v[206:209], v[68:71]
	v_mfma_f32_16x16x32_bf16 v[112:115], v[148:151], v[180:183], v[112:115]
	v_mfma_f32_16x16x32_bf16 v[116:119], v[156:159], v[180:183], v[116:119]
	v_mfma_f32_16x16x32_bf16 v[96:99], v[148:151], v[188:191], v[96:99]
	v_mfma_f32_16x16x32_bf16 v[100:103], v[156:159], v[188:191], v[100:103]
	v_mfma_f32_16x16x32_bf16 v[80:83], v[148:151], v[202:205], v[80:83]
	v_mfma_f32_16x16x32_bf16 v[84:87], v[156:159], v[202:205], v[84:87]
	v_mfma_f32_16x16x32_bf16 v[64:67], v[148:151], v[210:213], v[64:67]
	v_mfma_f32_16x16x32_bf16 v[68:71], v[156:159], v[210:213], v[68:71]
	s_barrier
	s_add_i32 s20, s51, s31
	s_mov_b32 m0, s20
	ds_read_b128 v[176:179], v197 offset:49152
	global_load_lds_dwordx4 v162, s[98:99]
	s_add_i32 m0, s20, 0x2000
	s_add_u32 s20, s22, 0xb0080
	s_addc_u32 s21, s23, 0
	s_add_i32 s22, s52, s31
	global_load_lds_dwordx4 v166, s[98:99]
	s_mov_b32 m0, s22
	ds_read_b128 v[180:183], v197 offset:50176
	global_load_lds_dwordx4 v162, s[20:21]
	s_add_i32 m0, s22, 0x2000
	ds_read_b128 v[184:187], v197 offset:51200
	global_load_lds_dwordx4 v166, s[20:21]
	s_mov_b32 m0, s39
	ds_read_b128 v[188:191], v197 offset:52224
	global_load_lds_dwordx4 v160, s[100:101]
	s_mov_b32 m0, s40
	ds_read_b128 v[198:201], v197 offset:53248
	global_load_lds_dwordx4 v164, s[100:101]
	ds_read_b128 v[202:205], v197 offset:54272
	ds_read_b128 v[206:209], v197 offset:55296
	ds_read_b128 v[210:213], v197 offset:56320
	s_waitcnt vmcnt(8)
	s_waitcnt lgkmcnt(0)
	s_barrier
	v_mfma_f32_16x16x32_bf16 v[56:59], v[128:131], v[176:179], v[56:59]
	v_mfma_f32_16x16x32_bf16 v[60:63], v[136:139], v[176:179], v[60:63]
	v_mfma_f32_16x16x32_bf16 v[40:43], v[128:131], v[184:187], v[40:43]
	v_mfma_f32_16x16x32_bf16 v[44:47], v[136:139], v[184:187], v[44:47]
	v_mfma_f32_16x16x32_bf16 v[24:27], v[128:131], v[198:201], v[24:27]
	v_mfma_f32_16x16x32_bf16 v[28:31], v[136:139], v[198:201], v[28:31]
	v_mfma_f32_16x16x32_bf16 v[8:11], v[128:131], v[206:209], v[8:11]
	v_mfma_f32_16x16x32_bf16 v[12:15], v[136:139], v[206:209], v[12:15]
	v_mfma_f32_16x16x32_bf16 v[56:59], v[132:135], v[180:183], v[56:59]
	v_mfma_f32_16x16x32_bf16 v[60:63], v[140:143], v[180:183], v[60:63]
	v_mfma_f32_16x16x32_bf16 v[40:43], v[132:135], v[188:191], v[40:43]
	v_mfma_f32_16x16x32_bf16 v[44:47], v[140:143], v[188:191], v[44:47]
	v_mfma_f32_16x16x32_bf16 v[24:27], v[132:135], v[202:205], v[24:27]
	v_mfma_f32_16x16x32_bf16 v[28:31], v[140:143], v[202:205], v[28:31]
	v_mfma_f32_16x16x32_bf16 v[8:11], v[132:135], v[210:213], v[8:11]
	v_mfma_f32_16x16x32_bf16 v[12:15], v[140:143], v[210:213], v[12:15]
	v_mfma_f32_16x16x32_bf16 v[48:51], v[144:147], v[176:179], v[48:51]
	v_mfma_f32_16x16x32_bf16 v[52:55], v[152:155], v[176:179], v[52:55]
	v_mfma_f32_16x16x32_bf16 v[32:35], v[144:147], v[184:187], v[32:35]
	v_mfma_f32_16x16x32_bf16 v[36:39], v[152:155], v[184:187], v[36:39]
	v_mfma_f32_16x16x32_bf16 v[16:19], v[144:147], v[198:201], v[16:19]
	v_mfma_f32_16x16x32_bf16 v[20:23], v[152:155], v[198:201], v[20:23]
	v_mfma_f32_16x16x32_bf16 v[4:7], v[144:147], v[206:209], v[4:7]
	v_mfma_f32_16x16x32_bf16 v[0:3], v[152:155], v[206:209], v[0:3]
	v_mfma_f32_16x16x32_bf16 v[48:51], v[148:151], v[180:183], v[48:51]
	v_mfma_f32_16x16x32_bf16 v[52:55], v[156:159], v[180:183], v[52:55]
	v_mfma_f32_16x16x32_bf16 v[32:35], v[148:151], v[188:191], v[32:35]
	v_mfma_f32_16x16x32_bf16 v[36:39], v[156:159], v[188:191], v[36:39]
	v_mfma_f32_16x16x32_bf16 v[16:19], v[148:151], v[202:205], v[16:19]
	v_mfma_f32_16x16x32_bf16 v[20:23], v[156:159], v[202:205], v[20:23]
	v_mfma_f32_16x16x32_bf16 v[4:7], v[148:151], v[210:213], v[4:7]
	v_mfma_f32_16x16x32_bf16 v[0:3], v[156:159], v[210:213], v[0:3]
	s_barrier
	s_add_i32 s50, s50, 2
	s_add_u32 s48, s48, 0x100
	s_addc_u32 s49, s49, 0
	s_mov_b64 s[20:21], s[2:3]
